# GEMM K-loops: B0 fragment LDS reads of phases 1/5 issued one phase early (12-read load segments become 8), counted vmcnt(10) guards
# baseline (speedup 1.0000x reference)
; #define PG8_STAGE(bufoff, gbase, voff) do { _Pragma("unroll") for (int _i = 0; _i < 2; ++_i) \
;         __builtin_amdgcn_global_load_lds((const unsigned*)((const char*)(gbase) + (voff)[_i]), (LAS unsigned*)(lds + (bufoff) + ldsw + _i * 8192), 16, 0, 0); } while (0)
; #define PG8_LDA(dst, b, h) do { _Pragma("unroll") for (int m = 0; m < 4; ++m) _Pragma("unroll") for (int k = 0; k < 2; ++k) dst[m][k] = *(const LAS bf16x8*)(lds + PG8_SA(b, h) + aoff + m * 2048 + k * 1024); } while (0)
; #define PG8_LDB(dst, b, h) do { _Pragma("unroll") for (int n = 0; n < 2; ++n) _Pragma("unroll") for (int k = 0; k < 2; ++k) dst[n][k] = *(const LAS bf16x8*)(lds + PG8_SB(b, h) + boff + n * 2048 + k * 1024); } while (0)
; #define PG8_MMA(ai, bj, At, Bt) do { __builtin_amdgcn_s_setprio(1); _Pragma("unroll") for (int m = 0; m < 4; ++m) _Pragma("unroll") for (int n = 0; n < 2; ++n) _Pragma("unroll") for (int k = 0; k < 2; ++k) \
;         acc[ai][bj][m][n] = __builtin_amdgcn_mfma_f32_16x16x32_bf16(Bt[n][k], At[m][k], acc[ai][bj][m][n], 0, 0, 0); __builtin_amdgcn_s_setprio(0); } while (0)
; #define PG8_WAIT_L(n) asm volatile("s_waitcnt lgkmcnt(" #n ")" ::: "memory")
; #define PG8_BAR __builtin_amdgcn_s_barrier()
; #define PG8_SCHED __builtin_amdgcn_sched_barrier(0)
; #define PG8_WAIT_L(n) asm volatile("s_waitcnt lgkmcnt(" #n ")" ::: "memory")
; #define PG8_BAR __builtin_amdgcn_s_barrier()
; #define PG8_SCHED __builtin_amdgcn_sched_barrier(0)
; template <class Epi, class Sched>
; DI void gemm_phase(LAS unsigned char* lds, const Gemm g, const Sched& S, const Epi& E) {
;     ...
;         const bool has_next = S.next(ui + 1, nxt);
;         const char* nA = has_next ? (const char*)g.A + (size_t)nxt.pm * tstepA : cA; const char* nB = has_next ? (const char*)g.Bt + (size_t)nxt.pn * tstepB : cB;
;         for (int t = 0; t < nt; t += 2) {
;             const bool last = (t == nt - 2);
;             const char* a1 = cA + (size_t)(t + 1) * kstep;
;             const char* a2 = last ? nA : cA + (size_t)(t + 2) * kstep; const char* b2 = last ? nB : cB + (size_t)(t + 2) * kstep;
;             const char* a3 = a2 + kstep; const char* b3 = b2 + kstep;
;             if (last && has_next) S.a_ready(nxt);
;             PG8_LDB(B0, 0, 0); PG8_SCHED; PG8_LDA(At, 0, 0); PG8_STAGE(PG8_SA(1, 1), a1 + hstepA, voffA);
;             PG8_WAIT_L(8); PG8_BAR; PG8_WAIT_L(0); PG8_MMA(0, 0, At, B0); PG8_BAR; PG8_SCHED;
.LBB0_230:
	s_ashr_i32 s45, s44, 31
	v_cmp_lt_i64_e32 vcc, s[6:7], v[204:205]
	s_lshl_b64 s[6:7], s[44:45], 19
	s_add_u32 s46, s21, s6
	s_addc_u32 s47, s22, s7
	s_and_b64 s[6:7], vcc, exec
	s_cselect_b32 s6, s47, s53
	s_cselect_b32 s7, s46, s52
	s_ashr_i32 s43, s42, 31
	s_lshl_b64 s[48:49], s[42:43], 19
	s_add_u32 s48, s2, s48
	s_addc_u32 s49, s3, s49
	s_and_b64 s[54:55], vcc, exec
	s_cselect_b32 s39, s49, s5
	s_cselect_b32 s43, s48, s4
	s_add_u32 s45, s4, 0x100
	s_addc_u32 s51, s5, 0
	s_add_u32 s4, s52, 0x40080
	v_mov_b32_e32 v2, 0
	s_addc_u32 s5, s53, 0
	s_mov_b32 s64, -2
	v_mov_b32_e32 v3, v2
	v_mov_b32_e32 v4, v2
	v_mov_b32_e32 v5, v2
	v_mov_b32_e32 v6, v2
	v_mov_b32_e32 v7, v2
	v_mov_b32_e32 v8, v2
	v_mov_b32_e32 v9, v2
	v_mov_b32_e32 v10, v2
	v_mov_b32_e32 v11, v2
	v_mov_b32_e32 v12, v2
	v_mov_b32_e32 v13, v2
	v_mov_b32_e32 v14, v2
	v_mov_b32_e32 v15, v2
	v_mov_b32_e32 v16, v2
	v_mov_b32_e32 v17, v2
	v_mov_b32_e32 v26, v2
	v_mov_b32_e32 v27, v2
	v_mov_b32_e32 v28, v2
	v_mov_b32_e32 v29, v2
	v_mov_b32_e32 v30, v2
	v_mov_b32_e32 v31, v2
	v_mov_b32_e32 v32, v2
	v_mov_b32_e32 v33, v2
	v_mov_b32_e32 v42, v2
	v_mov_b32_e32 v43, v2
	v_mov_b32_e32 v44, v2
	v_mov_b32_e32 v45, v2
	v_mov_b32_e32 v46, v2
	v_mov_b32_e32 v47, v2
	v_mov_b32_e32 v48, v2
	v_mov_b32_e32 v49, v2
	v_mov_b32_e32 v18, v2
	v_mov_b32_e32 v19, v2
	v_mov_b32_e32 v20, v2
	v_mov_b32_e32 v21, v2
	v_mov_b32_e32 v22, v2
	v_mov_b32_e32 v23, v2
	v_mov_b32_e32 v24, v2
	v_mov_b32_e32 v25, v2
	v_mov_b32_e32 v34, v2
	v_mov_b32_e32 v35, v2
	v_mov_b32_e32 v36, v2
	v_mov_b32_e32 v37, v2
	v_mov_b32_e32 v38, v2
	v_mov_b32_e32 v39, v2
	v_mov_b32_e32 v40, v2
	v_mov_b32_e32 v41, v2
	v_mov_b32_e32 v50, v2
	v_mov_b32_e32 v51, v2
	v_mov_b32_e32 v52, v2
	v_mov_b32_e32 v53, v2
	v_mov_b32_e32 v54, v2
	v_mov_b32_e32 v55, v2
	v_mov_b32_e32 v56, v2
	v_mov_b32_e32 v57, v2
	v_mov_b32_e32 v58, v2
	v_mov_b32_e32 v59, v2
	v_mov_b32_e32 v60, v2
	v_mov_b32_e32 v61, v2
	v_mov_b32_e32 v62, v2
	v_mov_b32_e32 v63, v2
	v_mov_b32_e32 v64, v2
	v_mov_b32_e32 v65, v2
	v_mov_b32_e32 v66, v2
	v_mov_b32_e32 v67, v2
	v_mov_b32_e32 v68, v2
	v_mov_b32_e32 v69, v2
	v_mov_b32_e32 v70, v2
	v_mov_b32_e32 v71, v2
	v_mov_b32_e32 v72, v2
	v_mov_b32_e32 v73, v2
	v_mov_b32_e32 v74, v2
	v_mov_b32_e32 v75, v2
	v_mov_b32_e32 v76, v2
	v_mov_b32_e32 v77, v2
	v_mov_b32_e32 v78, v2
	v_mov_b32_e32 v79, v2
	v_mov_b32_e32 v80, v2
	v_mov_b32_e32 v81, v2
	v_mov_b32_e32 v90, v2
	v_mov_b32_e32 v91, v2
	v_mov_b32_e32 v92, v2
	v_mov_b32_e32 v93, v2
	v_mov_b32_e32 v94, v2
	v_mov_b32_e32 v95, v2
	v_mov_b32_e32 v96, v2
	v_mov_b32_e32 v97, v2
	v_mov_b32_e32 v106, v2
	v_mov_b32_e32 v107, v2
	v_mov_b32_e32 v108, v2
	v_mov_b32_e32 v109, v2
	v_mov_b32_e32 v110, v2
	v_mov_b32_e32 v111, v2
	v_mov_b32_e32 v112, v2
	v_mov_b32_e32 v113, v2
	v_mov_b32_e32 v82, v2
	v_mov_b32_e32 v83, v2
	v_mov_b32_e32 v84, v2
	v_mov_b32_e32 v85, v2
	v_mov_b32_e32 v86, v2
	v_mov_b32_e32 v87, v2
	v_mov_b32_e32 v88, v2
	v_mov_b32_e32 v89, v2
	v_mov_b32_e32 v98, v2
	v_mov_b32_e32 v99, v2
	v_mov_b32_e32 v100, v2
	v_mov_b32_e32 v101, v2
	v_mov_b32_e32 v102, v2
	v_mov_b32_e32 v103, v2
	v_mov_b32_e32 v104, v2
	v_mov_b32_e32 v105, v2
	v_mov_b32_e32 v114, v2
	v_mov_b32_e32 v115, v2
	v_mov_b32_e32 v116, v2
	v_mov_b32_e32 v117, v2
	v_mov_b32_e32 v118, v2
	v_mov_b32_e32 v119, v2
	v_mov_b32_e32 v120, v2
	v_mov_b32_e32 v121, v2
	v_mov_b32_e32 v122, v2
	v_mov_b32_e32 v123, v2
	v_mov_b32_e32 v124, v2
	v_mov_b32_e32 v125, v2
	v_mov_b32_e32 v126, v2
	v_mov_b32_e32 v127, v2
	v_mov_b32_e32 v128, v2
	v_mov_b32_e32 v129, v2
	v_add_u32_e32 v158, 0x10000, v144
	ds_read_b128 v[146:149], v158
	ds_read_b128 v[150:153], v158 offset:1024
	ds_read_b128 v[154:157], v158 offset:2048
	ds_read_b128 v[158:161], v158 offset:3072
.LBB0_231:
	s_add_u32 s0, s4, 0xfffc0080
	s_addc_u32 s1, s5, -1
	s_add_i32 s11, 0, 0x10000
	s_cmp_eq_u32 s64, 12
	s_cselect_b32 s55, s6, s1
	s_cselect_b32 s54, s7, s0
	s_cselect_b32 s53, s39, s51
	s_cselect_b32 s52, s43, s45
	v_lshl_add_u64 v[194:195], s[4:5], 0, v[142:143]
	s_add_i32 m0, s56, 0xc000
	ds_read_b128 v[162:165], v145
	ds_read_b128 v[166:169], v145 offset:1024
	ds_read_b128 v[170:173], v145 offset:2048
	ds_read_b128 v[174:177], v145 offset:3072
	ds_read_b128 v[178:181], v145 offset:4096
	ds_read_b128 v[182:185], v145 offset:5120
	ds_read_b128 v[186:189], v145 offset:6144
	ds_read_b128 v[190:193], v145 offset:7168
	global_load_lds_dwordx4 v[194:195], off
	v_lshl_add_u64 v[194:195], s[4:5], 0, v[140:141]
	s_add_i32 m0, s56, 0xe000
	s_nop 0
	global_load_lds_dwordx4 v[194:195], off
	s_waitcnt lgkmcnt(8)
	s_barrier
	s_waitcnt lgkmcnt(0)
	s_setprio 1
	s_waitcnt lgkmcnt(0)
	v_mfma_f32_16x16x32_bf16 v[126:129], v[146:149], v[162:165], v[126:129]
	v_mfma_f32_16x16x32_bf16 v[122:125], v[154:157], v[162:165], v[122:125]
	v_mfma_f32_16x16x32_bf16 v[118:121], v[146:149], v[170:173], v[118:121]
	v_mfma_f32_16x16x32_bf16 v[114:117], v[154:157], v[170:173], v[114:117]
	v_mfma_f32_16x16x32_bf16 v[102:105], v[146:149], v[178:181], v[102:105]
	v_mfma_f32_16x16x32_bf16 v[98:101], v[154:157], v[178:181], v[98:101]
	v_mfma_f32_16x16x32_bf16 v[86:89], v[146:149], v[186:189], v[86:89]
	v_mfma_f32_16x16x32_bf16 v[82:85], v[154:157], v[186:189], v[82:85]
	v_mfma_f32_16x16x32_bf16 v[126:129], v[150:153], v[166:169], v[126:129]
	v_mfma_f32_16x16x32_bf16 v[122:125], v[158:161], v[166:169], v[122:125]
	v_mfma_f32_16x16x32_bf16 v[118:121], v[150:153], v[174:177], v[118:121]
	v_mfma_f32_16x16x32_bf16 v[114:117], v[158:161], v[174:177], v[114:117]
	v_mfma_f32_16x16x32_bf16 v[102:105], v[150:153], v[182:185], v[102:105]
	v_mfma_f32_16x16x32_bf16 v[98:101], v[158:161], v[182:185], v[98:101]
	v_mfma_f32_16x16x32_bf16 v[86:89], v[150:153], v[190:193], v[86:89]
	v_mfma_f32_16x16x32_bf16 v[82:85], v[158:161], v[190:193], v[82:85]
	s_setprio 0
	s_barrier
; #define PG8_STAGE(bufoff, gbase, voff) do { _Pragma("unroll") for (int _i = 0; _i < 2; ++_i) \
;         __builtin_amdgcn_global_load_lds((const unsigned*)((const char*)(gbase) + (voff)[_i]), (LAS unsigned*)(lds + (bufoff) + ldsw + _i * 8192), 16, 0, 0); } while (0)
; #define PG8_LDA(dst, b, h) do { _Pragma("unroll") for (int m = 0; m < 4; ++m) _Pragma("unroll") for (int k = 0; k < 2; ++k) dst[m][k] = *(const LAS bf16x8*)(lds + PG8_SA(b, h) + aoff + m * 2048 + k * 1024); } while (0)
; #define PG8_LDB(dst, b, h) do { _Pragma("unroll") for (int n = 0; n < 2; ++n) _Pragma("unroll") for (int k = 0; k < 2; ++k) dst[n][k] = *(const LAS bf16x8*)(lds + PG8_SB(b, h) + boff + n * 2048 + k * 1024); } while (0)
; #define PG8_MMA(ai, bj, At, Bt) do { __builtin_amdgcn_s_setprio(1); _Pragma("unroll") for (int m = 0; m < 4; ++m) _Pragma("unroll") for (int n = 0; n < 2; ++n) _Pragma("unroll") for (int k = 0; k < 2; ++k) \
;         acc[ai][bj][m][n] = __builtin_amdgcn_mfma_f32_16x16x32_bf16(Bt[n][k], At[m][k], acc[ai][bj][m][n], 0, 0, 0); __builtin_amdgcn_s_setprio(0); } while (0)
; #define PG8_WAIT_V(n) asm volatile("s_waitcnt vmcnt(" #n ")" ::: "memory")
; #define PG8_WAIT_L(n) asm volatile("s_waitcnt lgkmcnt(" #n ")" ::: "memory")
; #define PG8_BAR __builtin_amdgcn_s_barrier()
; #define PG8_SCHED __builtin_amdgcn_sched_barrier(0)
; #define PG8_WAIT_V(n) asm volatile("s_waitcnt vmcnt(" #n ")" ::: "memory")
; #define PG8_WAIT_L(n) asm volatile("s_waitcnt lgkmcnt(" #n ")" ::: "memory")
; #define PG8_BAR __builtin_amdgcn_s_barrier()
; template <class Epi, class Sched>
; DI void gemm_phase(LAS unsigned char* lds, const Gemm g, const Sched& S, const Epi& E) {
;     ...
;             PG8_WAIT_L(8); PG8_BAR; PG8_WAIT_L(0); PG8_MMA(0, 0, At, B0); PG8_BAR; PG8_SCHED;
;             PG8_LDB(B1, 0, 1); PG8_STAGE(PG8_SB(0, 0), b2, voffB);
;             PG8_BAR; PG8_WAIT_L(0); PG8_MMA(0, 1, At, B1); PG8_BAR;
;             PG8_LDA(At, 0, 1); PG8_STAGE(PG8_SA(0, 0), a2, voffA);
;             PG8_BAR; PG8_WAIT_L(0); PG8_MMA(1, 0, At, B0); PG8_BAR; PG8_SCHED;
;             PG8_STAGE(PG8_SB(0, 1), b2 + hstepB, voffB);
;             PG8_WAIT_V(6); PG8_BAR; PG8_MMA(1, 1, At, B1); PG8_BAR;
;             PG8_LDB(B0, 1, 0); PG8_SCHED; PG8_LDA(At, 1, 0); PG8_STAGE(PG8_SA(0, 1), a2 + hstepA, voffA);
;             PG8_WAIT_L(8); PG8_BAR; PG8_WAIT_L(0); PG8_MMA(0, 0, At, B0); PG8_BAR; PG8_SCHED;
	s_add_i32 s0, 0, 0x14000
	v_add_u32_e32 v198, s0, v144
	s_add_i32 s1, s11, s23
	ds_read_b128 v[194:197], v198
	ds_read_b128 v[210:213], v198 offset:1024
	ds_read_b128 v[214:217], v198 offset:2048
	ds_read_b128 v[218:221], v198 offset:3072
	v_lshl_add_u64 v[198:199], s[52:53], 0, v[132:133]
	s_mov_b32 m0, s1
	v_lshl_add_u64 v[230:231], s[52:53], 0, v[136:137]
	global_load_lds_dwordx4 v[198:199], off
	s_add_i32 m0, s1, 0x2000
	s_nop 0
	global_load_lds_dwordx4 v[230:231], off
	s_barrier
	s_waitcnt lgkmcnt(0)
	s_setprio 1
	s_waitcnt lgkmcnt(0)
	v_mfma_f32_16x16x32_bf16 v[110:113], v[194:197], v[162:165], v[110:113]
	v_mfma_f32_16x16x32_bf16 v[106:109], v[214:217], v[162:165], v[106:109]
	v_mfma_f32_16x16x32_bf16 v[94:97], v[194:197], v[170:173], v[94:97]
	v_mfma_f32_16x16x32_bf16 v[90:93], v[214:217], v[170:173], v[90:93]
	v_mfma_f32_16x16x32_bf16 v[78:81], v[194:197], v[178:181], v[78:81]
	v_mfma_f32_16x16x32_bf16 v[74:77], v[214:217], v[178:181], v[74:77]
	v_mfma_f32_16x16x32_bf16 v[70:73], v[194:197], v[186:189], v[70:73]
	v_mfma_f32_16x16x32_bf16 v[66:69], v[214:217], v[186:189], v[66:69]
	v_mfma_f32_16x16x32_bf16 v[110:113], v[210:213], v[166:169], v[110:113]
	v_mfma_f32_16x16x32_bf16 v[106:109], v[218:221], v[166:169], v[106:109]
	v_mfma_f32_16x16x32_bf16 v[94:97], v[210:213], v[174:177], v[94:97]
	v_mfma_f32_16x16x32_bf16 v[90:93], v[218:221], v[174:177], v[90:93]
	v_mfma_f32_16x16x32_bf16 v[78:81], v[210:213], v[182:185], v[78:81]
	v_mfma_f32_16x16x32_bf16 v[74:77], v[218:221], v[182:185], v[74:77]
	v_mfma_f32_16x16x32_bf16 v[70:73], v[210:213], v[190:193], v[70:73]
	v_mfma_f32_16x16x32_bf16 v[66:69], v[218:221], v[190:193], v[66:69]
	s_setprio 0
	s_mov_b32 m0, s56
	v_lshl_add_u64 v[232:233], s[54:55], 0, v[130:131]
	s_barrier
	ds_read_b128 v[162:165], v145 offset:16384
	ds_read_b128 v[166:169], v145 offset:17408
	ds_read_b128 v[170:173], v145 offset:18432
	ds_read_b128 v[174:177], v145 offset:19456
	ds_read_b128 v[178:181], v145 offset:20480
	ds_read_b128 v[182:185], v145 offset:21504
	ds_read_b128 v[186:189], v145 offset:22528
	ds_read_b128 v[190:193], v145 offset:23552
	global_load_lds_dwordx4 v[232:233], off
	v_lshl_add_u64 v[234:235], s[54:55], 0, v[134:135]
	s_mov_b32 m0, s57
	s_nop 0
	global_load_lds_dwordx4 v[234:235], off
	s_waitcnt vmcnt(10)
	s_barrier
	s_waitcnt lgkmcnt(0)
	s_setprio 1
	s_waitcnt lgkmcnt(0)
	v_mfma_f32_16x16x32_bf16 v[62:65], v[146:149], v[162:165], v[62:65]
	v_mfma_f32_16x16x32_bf16 v[58:61], v[154:157], v[162:165], v[58:61]
	v_mfma_f32_16x16x32_bf16 v[54:57], v[146:149], v[170:173], v[54:57]
	v_mfma_f32_16x16x32_bf16 v[50:53], v[154:157], v[170:173], v[50:53]
	v_mfma_f32_16x16x32_bf16 v[38:41], v[146:149], v[178:181], v[38:41]
	v_mfma_f32_16x16x32_bf16 v[34:37], v[154:157], v[178:181], v[34:37]
	v_mfma_f32_16x16x32_bf16 v[22:25], v[146:149], v[186:189], v[22:25]
	v_mfma_f32_16x16x32_bf16 v[18:21], v[154:157], v[186:189], v[18:21]
	v_mfma_f32_16x16x32_bf16 v[62:65], v[150:153], v[166:169], v[62:65]
	v_mfma_f32_16x16x32_bf16 v[58:61], v[158:161], v[166:169], v[58:61]
	v_mfma_f32_16x16x32_bf16 v[54:57], v[150:153], v[174:177], v[54:57]
	v_mfma_f32_16x16x32_bf16 v[50:53], v[158:161], v[174:177], v[50:53]
	v_mfma_f32_16x16x32_bf16 v[38:41], v[150:153], v[182:185], v[38:41]
	v_mfma_f32_16x16x32_bf16 v[34:37], v[158:161], v[182:185], v[34:37]
	v_mfma_f32_16x16x32_bf16 v[22:25], v[150:153], v[190:193], v[22:25]
	v_mfma_f32_16x16x32_bf16 v[18:21], v[158:161], v[190:193], v[18:21]
	s_setprio 0
	s_barrier
	s_add_u32 s66, s52, 0x40000
	s_addc_u32 s67, s53, 0
	s_add_i32 s0, s0, s23
	v_lshl_add_u64 v[146:147], s[66:67], 0, v[132:133]
	s_mov_b32 m0, s0
	s_nop 0
	global_load_lds_dwordx4 v[146:147], off
	v_lshl_add_u64 v[146:147], s[66:67], 0, v[136:137]
	s_add_i32 m0, s0, 0x2000
	s_nop 0
	global_load_lds_dwordx4 v[146:147], off
	v_add_u32_e32 v158, 0x18000, v144
	ds_read_b128 v[146:149], v158
	ds_read_b128 v[150:153], v158 offset:1024
	ds_read_b128 v[154:157], v158 offset:2048
	ds_read_b128 v[158:161], v158 offset:3072
	s_waitcnt vmcnt(6)
	s_barrier
	s_setprio 1
	v_mfma_f32_16x16x32_bf16 v[46:49], v[194:197], v[162:165], v[46:49]
	v_mfma_f32_16x16x32_bf16 v[42:45], v[214:217], v[162:165], v[42:45]
	v_mfma_f32_16x16x32_bf16 v[30:33], v[194:197], v[170:173], v[30:33]
	v_mfma_f32_16x16x32_bf16 v[26:29], v[214:217], v[170:173], v[26:29]
	v_mfma_f32_16x16x32_bf16 v[14:17], v[194:197], v[178:181], v[14:17]
	v_mfma_f32_16x16x32_bf16 v[10:13], v[214:217], v[178:181], v[10:13]
	v_mfma_f32_16x16x32_bf16 v[6:9], v[194:197], v[186:189], v[6:9]
	v_mfma_f32_16x16x32_bf16 v[2:5], v[214:217], v[186:189], v[2:5]
	v_mfma_f32_16x16x32_bf16 v[46:49], v[210:213], v[166:169], v[46:49]
	v_mfma_f32_16x16x32_bf16 v[42:45], v[218:221], v[166:169], v[42:45]
	v_mfma_f32_16x16x32_bf16 v[30:33], v[210:213], v[174:177], v[30:33]
	v_mfma_f32_16x16x32_bf16 v[26:29], v[218:221], v[174:177], v[26:29]
	v_mfma_f32_16x16x32_bf16 v[14:17], v[210:213], v[182:185], v[14:17]
	v_mfma_f32_16x16x32_bf16 v[10:13], v[218:221], v[182:185], v[10:13]
	v_mfma_f32_16x16x32_bf16 v[6:9], v[210:213], v[190:193], v[6:9]
	v_mfma_f32_16x16x32_bf16 v[2:5], v[218:221], v[190:193], v[2:5]
	s_setprio 0
	s_add_i32 s0, 0, 0x18000
	s_barrier
	s_add_u32 s54, s54, 0x40000
	s_addc_u32 s55, s55, 0
	s_mov_b32 m0, s58
	v_lshl_add_u64 v[194:195], s[54:55], 0, v[130:131]
	ds_read_b128 v[162:165], v145 offset:32768
	ds_read_b128 v[166:169], v145 offset:33792
	ds_read_b128 v[170:173], v145 offset:34816
	ds_read_b128 v[174:177], v145 offset:35840
	ds_read_b128 v[178:181], v145 offset:36864
	ds_read_b128 v[182:185], v145 offset:37888
	ds_read_b128 v[186:189], v145 offset:38912
	ds_read_b128 v[190:193], v145 offset:39936
	global_load_lds_dwordx4 v[194:195], off
	v_lshl_add_u64 v[194:195], s[54:55], 0, v[134:135]
	s_mov_b32 m0, s59
	s_nop 0
	global_load_lds_dwordx4 v[194:195], off
	s_waitcnt lgkmcnt(8)
	s_barrier
; #define PG8_STAGE(bufoff, gbase, voff) do { _Pragma("unroll") for (int _i = 0; _i < 2; ++_i) \
;         __builtin_amdgcn_global_load_lds((const unsigned*)((const char*)(gbase) + (voff)[_i]), (LAS unsigned*)(lds + (bufoff) + ldsw + _i * 8192), 16, 0, 0); } while (0)
; #define PG8_LDA(dst, b, h) do { _Pragma("unroll") for (int m = 0; m < 4; ++m) _Pragma("unroll") for (int k = 0; k < 2; ++k) dst[m][k] = *(const LAS bf16x8*)(lds + PG8_SA(b, h) + aoff + m * 2048 + k * 1024); } while (0)
; #define PG8_LDB(dst, b, h) do { _Pragma("unroll") for (int n = 0; n < 2; ++n) _Pragma("unroll") for (int k = 0; k < 2; ++k) dst[n][k] = *(const LAS bf16x8*)(lds + PG8_SB(b, h) + boff + n * 2048 + k * 1024); } while (0)
; #define PG8_MMA(ai, bj, At, Bt) do { __builtin_amdgcn_s_setprio(1); _Pragma("unroll") for (int m = 0; m < 4; ++m) _Pragma("unroll") for (int n = 0; n < 2; ++n) _Pragma("unroll") for (int k = 0; k < 2; ++k) \
;         acc[ai][bj][m][n] = __builtin_amdgcn_mfma_f32_16x16x32_bf16(Bt[n][k], At[m][k], acc[ai][bj][m][n], 0, 0, 0); __builtin_amdgcn_s_setprio(0); } while (0)
; #define PG8_WAIT_V(n) asm volatile("s_waitcnt vmcnt(" #n ")" ::: "memory")
; #define PG8_WAIT_L(n) asm volatile("s_waitcnt lgkmcnt(" #n ")" ::: "memory")
; #define PG8_BAR __builtin_amdgcn_s_barrier()
; #define PG8_SCHED __builtin_amdgcn_sched_barrier(0)
; #define PG8_LDA(dst, b, h) do { _Pragma("unroll") for (int m = 0; m < 4; ++m) _Pragma("unroll") for (int k = 0; k < 2; ++k) dst[m][k] = *(const LAS bf16x8*)(lds + PG8_SA(b, h) + aoff + m * 2048 + k * 1024); } while (0)
; #define PG8_WAIT_V(n) asm volatile("s_waitcnt vmcnt(" #n ")" ::: "memory")
; #define PG8_WAIT_L(n) asm volatile("s_waitcnt lgkmcnt(" #n ")" ::: "memory")
; template <class Epi, class Sched>
; DI void gemm_phase(LAS unsigned char* lds, const Gemm g, const Sched& S, const Epi& E) {
;     ...
;             PG8_WAIT_L(8); PG8_BAR; PG8_WAIT_L(0); PG8_MMA(0, 0, At, B0); PG8_BAR; PG8_SCHED;
;             PG8_LDB(B1, 1, 1); PG8_STAGE(PG8_SB(1, 0), b3, voffB);
;             PG8_BAR; PG8_WAIT_L(0); PG8_MMA(0, 1, At, B1); PG8_BAR;
;             PG8_LDA(At, 1, 1); PG8_STAGE(PG8_SA(1, 0), a3, voffA);
;             PG8_BAR; PG8_WAIT_L(0); PG8_MMA(1, 0, At, B0); PG8_BAR; PG8_SCHED;
;             PG8_STAGE(PG8_SB(1, 1), b3 + hstepB, voffB);
;             PG8_WAIT_V(6); PG8_BAR; PG8_MMA(1, 1, At, B1); PG8_BAR;
;         }
	s_waitcnt lgkmcnt(0)
	s_setprio 1
	s_waitcnt lgkmcnt(0)
	v_mfma_f32_16x16x32_bf16 v[126:129], v[146:149], v[162:165], v[126:129]
	v_mfma_f32_16x16x32_bf16 v[122:125], v[154:157], v[162:165], v[122:125]
	v_mfma_f32_16x16x32_bf16 v[118:121], v[146:149], v[170:173], v[118:121]
	v_mfma_f32_16x16x32_bf16 v[114:117], v[154:157], v[170:173], v[114:117]
	v_mfma_f32_16x16x32_bf16 v[102:105], v[146:149], v[178:181], v[102:105]
	v_mfma_f32_16x16x32_bf16 v[98:101], v[154:157], v[178:181], v[98:101]
	v_mfma_f32_16x16x32_bf16 v[86:89], v[146:149], v[186:189], v[86:89]
	v_mfma_f32_16x16x32_bf16 v[82:85], v[154:157], v[186:189], v[82:85]
	v_mfma_f32_16x16x32_bf16 v[126:129], v[150:153], v[166:169], v[126:129]
	v_mfma_f32_16x16x32_bf16 v[122:125], v[158:161], v[166:169], v[122:125]
	v_mfma_f32_16x16x32_bf16 v[118:121], v[150:153], v[174:177], v[118:121]
	v_mfma_f32_16x16x32_bf16 v[114:117], v[158:161], v[174:177], v[114:117]
	v_mfma_f32_16x16x32_bf16 v[102:105], v[150:153], v[182:185], v[102:105]
	v_mfma_f32_16x16x32_bf16 v[98:101], v[158:161], v[182:185], v[98:101]
	v_mfma_f32_16x16x32_bf16 v[86:89], v[150:153], v[190:193], v[86:89]
	v_mfma_f32_16x16x32_bf16 v[82:85], v[158:161], v[190:193], v[82:85]
	s_setprio 0
	s_barrier
	s_add_i32 s1, 0, 0x1c000
	s_add_i32 s0, s0, s23
	v_add_u32_e32 v218, s1, v144
	v_lshl_add_u64 v[198:199], v[198:199], 0, s[16:17]
	s_mov_b32 m0, s0
	ds_read_b128 v[194:197], v218
	ds_read_b128 v[210:213], v218 offset:1024
	ds_read_b128 v[214:217], v218 offset:2048
	ds_read_b128 v[218:221], v218 offset:3072
	global_load_lds_dwordx4 v[198:199], off
	v_lshl_add_u64 v[198:199], v[230:231], 0, s[16:17]
	s_add_i32 m0, s0, 0x2000
	s_nop 0
	global_load_lds_dwordx4 v[198:199], off
	s_barrier
	s_waitcnt lgkmcnt(0)
	s_setprio 1
	s_waitcnt lgkmcnt(0)
	v_mfma_f32_16x16x32_bf16 v[110:113], v[194:197], v[162:165], v[110:113]
	v_mfma_f32_16x16x32_bf16 v[106:109], v[214:217], v[162:165], v[106:109]
	v_mfma_f32_16x16x32_bf16 v[94:97], v[194:197], v[170:173], v[94:97]
	v_mfma_f32_16x16x32_bf16 v[90:93], v[214:217], v[170:173], v[90:93]
	v_mfma_f32_16x16x32_bf16 v[78:81], v[194:197], v[178:181], v[78:81]
	v_mfma_f32_16x16x32_bf16 v[74:77], v[214:217], v[178:181], v[74:77]
	v_mfma_f32_16x16x32_bf16 v[70:73], v[194:197], v[186:189], v[70:73]
	v_mfma_f32_16x16x32_bf16 v[66:69], v[214:217], v[186:189], v[66:69]
	v_mfma_f32_16x16x32_bf16 v[110:113], v[210:213], v[166:169], v[110:113]
	v_mfma_f32_16x16x32_bf16 v[106:109], v[218:221], v[166:169], v[106:109]
	v_mfma_f32_16x16x32_bf16 v[94:97], v[210:213], v[174:177], v[94:97]
	v_mfma_f32_16x16x32_bf16 v[90:93], v[218:221], v[174:177], v[90:93]
	v_mfma_f32_16x16x32_bf16 v[78:81], v[210:213], v[182:185], v[78:81]
	v_mfma_f32_16x16x32_bf16 v[74:77], v[218:221], v[182:185], v[74:77]
	v_mfma_f32_16x16x32_bf16 v[70:73], v[210:213], v[190:193], v[70:73]
	v_mfma_f32_16x16x32_bf16 v[66:69], v[218:221], v[190:193], v[66:69]
	s_setprio 0
	s_mov_b32 m0, s60
	v_lshl_add_u64 v[198:199], v[232:233], 0, s[16:17]
	s_barrier
	ds_read_b128 v[162:165], v145 offset:49152
	ds_read_b128 v[166:169], v145 offset:50176
	ds_read_b128 v[170:173], v145 offset:51200
	ds_read_b128 v[174:177], v145 offset:52224
	ds_read_b128 v[178:181], v145 offset:53248
	ds_read_b128 v[182:185], v145 offset:54272
	ds_read_b128 v[186:189], v145 offset:55296
	ds_read_b128 v[190:193], v145 offset:56320
	global_load_lds_dwordx4 v[198:199], off
	v_lshl_add_u64 v[198:199], v[234:235], 0, s[16:17]
	s_mov_b32 m0, s61
	s_nop 0
	global_load_lds_dwordx4 v[198:199], off
	s_waitcnt vmcnt(10)
	s_barrier
	s_waitcnt lgkmcnt(0)
	s_setprio 1
	s_waitcnt lgkmcnt(0)
	v_mfma_f32_16x16x32_bf16 v[62:65], v[146:149], v[162:165], v[62:65]
	v_mfma_f32_16x16x32_bf16 v[58:61], v[154:157], v[162:165], v[58:61]
	v_mfma_f32_16x16x32_bf16 v[54:57], v[146:149], v[170:173], v[54:57]
	v_mfma_f32_16x16x32_bf16 v[50:53], v[154:157], v[170:173], v[50:53]
	v_mfma_f32_16x16x32_bf16 v[38:41], v[146:149], v[178:181], v[38:41]
	v_mfma_f32_16x16x32_bf16 v[34:37], v[154:157], v[178:181], v[34:37]
	v_mfma_f32_16x16x32_bf16 v[22:25], v[146:149], v[186:189], v[22:25]
	v_mfma_f32_16x16x32_bf16 v[18:21], v[154:157], v[186:189], v[18:21]
	v_mfma_f32_16x16x32_bf16 v[62:65], v[150:153], v[166:169], v[62:65]
	v_mfma_f32_16x16x32_bf16 v[58:61], v[158:161], v[166:169], v[58:61]
	v_mfma_f32_16x16x32_bf16 v[54:57], v[150:153], v[174:177], v[54:57]
	v_mfma_f32_16x16x32_bf16 v[50:53], v[158:161], v[174:177], v[50:53]
	v_mfma_f32_16x16x32_bf16 v[38:41], v[150:153], v[182:185], v[38:41]
	v_mfma_f32_16x16x32_bf16 v[34:37], v[158:161], v[182:185], v[34:37]
	v_mfma_f32_16x16x32_bf16 v[22:25], v[150:153], v[190:193], v[22:25]
	v_mfma_f32_16x16x32_bf16 v[18:21], v[158:161], v[190:193], v[18:21]
	s_setprio 0
	s_barrier
	s_add_u32 s52, s52, 0x40080
	s_addc_u32 s53, s53, 0
	s_add_i32 s0, s1, s23
	v_lshl_add_u64 v[146:147], s[52:53], 0, v[132:133]
	s_mov_b32 m0, s0
	s_nop 0
	global_load_lds_dwordx4 v[146:147], off
	v_lshl_add_u64 v[146:147], s[52:53], 0, v[136:137]
	s_add_i32 m0, s0, 0x2000
	s_nop 0
	global_load_lds_dwordx4 v[146:147], off
	v_add_u32_e32 v158, 0x10000, v144
	ds_read_b128 v[146:149], v158
	ds_read_b128 v[150:153], v158 offset:1024
	ds_read_b128 v[154:157], v158 offset:2048
	ds_read_b128 v[158:161], v158 offset:3072
	s_waitcnt vmcnt(6)
	s_barrier
	s_setprio 1
	v_mfma_f32_16x16x32_bf16 v[46:49], v[194:197], v[162:165], v[46:49]
	v_mfma_f32_16x16x32_bf16 v[42:45], v[214:217], v[162:165], v[42:45]
	v_mfma_f32_16x16x32_bf16 v[30:33], v[194:197], v[170:173], v[30:33]
	v_mfma_f32_16x16x32_bf16 v[26:29], v[214:217], v[170:173], v[26:29]
	v_mfma_f32_16x16x32_bf16 v[14:17], v[194:197], v[178:181], v[14:17]
	v_mfma_f32_16x16x32_bf16 v[10:13], v[214:217], v[178:181], v[10:13]
	v_mfma_f32_16x16x32_bf16 v[6:9], v[194:197], v[186:189], v[6:9]
	v_mfma_f32_16x16x32_bf16 v[2:5], v[214:217], v[186:189], v[2:5]
	v_mfma_f32_16x16x32_bf16 v[46:49], v[210:213], v[166:169], v[46:49]
	v_mfma_f32_16x16x32_bf16 v[42:45], v[218:221], v[166:169], v[42:45]
	v_mfma_f32_16x16x32_bf16 v[30:33], v[210:213], v[174:177], v[30:33]
	v_mfma_f32_16x16x32_bf16 v[26:29], v[218:221], v[174:177], v[26:29]
	v_mfma_f32_16x16x32_bf16 v[14:17], v[210:213], v[182:185], v[14:17]
	v_mfma_f32_16x16x32_bf16 v[10:13], v[218:221], v[182:185], v[10:13]
	v_mfma_f32_16x16x32_bf16 v[6:9], v[210:213], v[190:193], v[6:9]
	v_mfma_f32_16x16x32_bf16 v[2:5], v[218:221], v[190:193], v[2:5]
	s_setprio 0
	s_add_i32 s64, s64, 2
	s_add_u32 s45, s45, 0x100
	s_addc_u32 s51, s51, 0
	s_add_u32 s4, s4, 0x100
	s_addc_u32 s5, s5, 0
	s_cmp_gt_u32 s64, 13
	s_barrier
	s_cbranch_scc0 .LBB0_231
	s_waitcnt lgkmcnt(0)
	s_cmp_lt_i32 s38, 4
	s_cbranch_scc1 .LBB0_236
	s_cmp_eq_u32 s38, 4
	s_mov_b64 s[4:5], -1
	s_cbranch_scc0 .LBB0_235
	s_mov_b64 s[4:5], 0

; #define PG8_LDA(dst, b, h) do { _Pragma("unroll") for (int m = 0; m < 4; ++m) _Pragma("unroll") for (int k = 0; k < 2; ++k) dst[m][k] = *(const LAS bf16x8*)(lds + PG8_SA(b, h) + aoff + m * 2048 + k * 1024); } while (0)
; #define PG8_LDB(dst, b, h) do { _Pragma("unroll") for (int n = 0; n < 2; ++n) _Pragma("unroll") for (int k = 0; k < 2; ++k) dst[n][k] = *(const LAS bf16x8*)(lds + PG8_SB(b, h) + boff + n * 2048 + k * 1024); } while (0)
; #define PG8_MMA(ai, bj, At, Bt) do { __builtin_amdgcn_s_setprio(1); _Pragma("unroll") for (int m = 0; m < 4; ++m) _Pragma("unroll") for (int n = 0; n < 2; ++n) _Pragma("unroll") for (int k = 0; k < 2; ++k) \
;         acc[ai][bj][m][n] = __builtin_amdgcn_mfma_f32_16x16x32_bf16(Bt[n][k], At[m][k], acc[ai][bj][m][n], 0, 0, 0); __builtin_amdgcn_s_setprio(0); } while (0)
; #define PG8_WAIT_L(n) asm volatile("s_waitcnt lgkmcnt(" #n ")" ::: "memory")
; #define PG8_BAR __builtin_amdgcn_s_barrier()
; #define PG8_SCHED __builtin_amdgcn_sched_barrier(0)
; #define PG8_WAIT_L(n) asm volatile("s_waitcnt lgkmcnt(" #n ")" ::: "memory")
; #define PG8_BAR __builtin_amdgcn_s_barrier()
; #define PG8_SCHED __builtin_amdgcn_sched_barrier(0)
; DI void gemm_phase_p5(LAS unsigned char* lds, const Unit u, const bf16_t* hb, const bf16_t* xn, const bf16_t* wtm, const bf16_t* wtp,
;                       char* scr, bf16_t* mixed, const float* bmerge) {
;     ...
;         for (int t = 0; t < nt; t += 2) {
;             const bool last = (t == nt - 2);
;             const char* a1 = cur.A + (size_t)(t + 1) * kstep;
;             const char* a2 = last ? nxt.A : cur.A + (size_t)(t + 2) * kstep; const char* b2 = last ? nxt.B : cur.B + (size_t)(t + 2) * kstep;
;             const unsigned ld2 = last ? ldn : ldc; const size_t hs2 = last ? hsn : hsc;
;             const char* a3 = a2 + kstep; const char* b3 = b2 + kstep;
;             PG8_LDB(B0, 0, 0); PG8_SCHED; PG8_LDA(At, 0, 0); PG8_STAGE2(PG8_SA(1, 1), a1 + hsc, rowA, ldc);
;             PG8_WAIT_L(8); PG8_BAR; PG8_WAIT_L(0); PG8_MMA(0, 0, At, B0); PG8_BAR; PG8_SCHED;
;     ...
; #pragma unroll
;         for (int a = 0; a < 2; ++a)
; #pragma unroll
;             for (int b = 0; b < 2; ++b)
; #pragma unroll
;                 for (int m = 0; m < 4; ++m)
; #pragma unroll
;                     for (int n = 0; n < 2; ++n) acc[a][b][m][n] = (f32x4){0.f, 0.f, 0.f, 0.f};
;         cur = nxt; ldc = ldn; hsc = hsn;
.LBB0_937:
	s_cmp_eq_u32 s78, 0
	s_movk_i32 s0, 0x800
	s_cselect_b32 s21, s0, 0x1e00
	s_mov_b32 s0, 0xf0000
	s_cselect_b32 s46, 0x40000, s0
	s_add_i32 s6, s10, -2
	s_lshl_b32 s0, s80, 6
	s_add_u32 s7, s50, 0x100
	s_addc_u32 s81, s51, 0
	s_add_u32 s11, s48, s0
	s_addc_u32 s50, s49, 0
	v_mad_u64_u32 v[2:3], s[0:1], s80, v179, v[182:183]
	s_add_u32 s0, s36, s11
	v_mov_b32_e32 v3, v1
	s_addc_u32 s1, s37, s50
	v_lshl_add_u64 v[4:5], s[0:1], 0, v[2:3]
	s_add_u32 s0, s36, s48
	s_addc_u32 s1, s37, s49
	s_mov_b32 s47, 0
	v_lshl_add_u64 v[132:133], s[0:1], 0, v[2:3]
	v_mov_b32_e32 v2, 0
	v_lshl_add_u64 v[130:131], v[4:5], 0, s[16:17]
	s_mov_b64 s[50:51], 0
	s_mov_b32 s52, s47
	v_mov_b32_e32 v3, v2
	v_mov_b32_e32 v4, v2
	v_mov_b32_e32 v5, v2
	v_mov_b32_e32 v6, v2
	v_mov_b32_e32 v7, v2
	v_mov_b32_e32 v8, v2
	v_mov_b32_e32 v9, v2
	v_mov_b32_e32 v18, v2
	v_mov_b32_e32 v19, v2
	v_mov_b32_e32 v20, v2
	v_mov_b32_e32 v21, v2
	v_mov_b32_e32 v22, v2
	v_mov_b32_e32 v23, v2
	v_mov_b32_e32 v24, v2
	v_mov_b32_e32 v25, v2
	v_mov_b32_e32 v34, v2
	v_mov_b32_e32 v35, v2
	v_mov_b32_e32 v36, v2
	v_mov_b32_e32 v37, v2
	v_mov_b32_e32 v38, v2
	v_mov_b32_e32 v39, v2
	v_mov_b32_e32 v40, v2
	v_mov_b32_e32 v41, v2
	v_mov_b32_e32 v50, v2
	v_mov_b32_e32 v51, v2
	v_mov_b32_e32 v52, v2
	v_mov_b32_e32 v53, v2
	v_mov_b32_e32 v54, v2
	v_mov_b32_e32 v55, v2
	v_mov_b32_e32 v56, v2
	v_mov_b32_e32 v57, v2
	v_mov_b32_e32 v10, v2
	v_mov_b32_e32 v11, v2
	v_mov_b32_e32 v12, v2
	v_mov_b32_e32 v13, v2
	v_mov_b32_e32 v14, v2
	v_mov_b32_e32 v15, v2
	v_mov_b32_e32 v16, v2
	v_mov_b32_e32 v17, v2
	v_mov_b32_e32 v26, v2
	v_mov_b32_e32 v27, v2
	v_mov_b32_e32 v28, v2
	v_mov_b32_e32 v29, v2
	v_mov_b32_e32 v30, v2
	s_waitcnt vmcnt(0)
	v_mov_b32_e32 v31, v2
	v_mov_b32_e32 v32, v2
	v_mov_b32_e32 v33, v2
	v_mov_b32_e32 v42, v2
	v_mov_b32_e32 v43, v2
	v_mov_b32_e32 v44, v2
	v_mov_b32_e32 v45, v2
	v_mov_b32_e32 v46, v2
	v_mov_b32_e32 v47, v2
	v_mov_b32_e32 v48, v2
	v_mov_b32_e32 v49, v2
	v_mov_b32_e32 v58, v2
	v_mov_b32_e32 v59, v2
	v_mov_b32_e32 v60, v2
	v_mov_b32_e32 v61, v2
	v_mov_b32_e32 v62, v2
	v_mov_b32_e32 v63, v2
	v_mov_b32_e32 v64, v2
	v_mov_b32_e32 v65, v2
	v_mov_b32_e32 v66, v2
	v_mov_b32_e32 v67, v2
	v_mov_b32_e32 v68, v2
	v_mov_b32_e32 v69, v2
	v_mov_b32_e32 v70, v2
	v_mov_b32_e32 v71, v2
	v_mov_b32_e32 v72, v2
	v_mov_b32_e32 v73, v2
	v_mov_b32_e32 v82, v2
	v_mov_b32_e32 v83, v2
	v_mov_b32_e32 v84, v2
	v_mov_b32_e32 v85, v2
	v_mov_b32_e32 v86, v2
	v_mov_b32_e32 v87, v2
	v_mov_b32_e32 v88, v2
	v_mov_b32_e32 v89, v2
	v_mov_b32_e32 v98, v2
	v_mov_b32_e32 v99, v2
	v_mov_b32_e32 v100, v2
	v_mov_b32_e32 v101, v2
	v_mov_b32_e32 v102, v2
	v_mov_b32_e32 v103, v2
	v_mov_b32_e32 v104, v2
	v_mov_b32_e32 v105, v2
	v_mov_b32_e32 v114, v2
	v_mov_b32_e32 v115, v2
	v_mov_b32_e32 v116, v2
	v_mov_b32_e32 v117, v2
	v_mov_b32_e32 v118, v2
	v_mov_b32_e32 v119, v2
	v_mov_b32_e32 v120, v2
	v_mov_b32_e32 v121, v2
	v_mov_b32_e32 v74, v2
	v_mov_b32_e32 v75, v2
	v_mov_b32_e32 v76, v2
	v_mov_b32_e32 v77, v2
	v_mov_b32_e32 v78, v2
	v_mov_b32_e32 v79, v2
	v_mov_b32_e32 v80, v2
	v_mov_b32_e32 v81, v2
	v_mov_b32_e32 v90, v2
	v_mov_b32_e32 v91, v2
	v_mov_b32_e32 v92, v2
	v_mov_b32_e32 v93, v2
	v_mov_b32_e32 v94, v2
	v_mov_b32_e32 v95, v2
	v_mov_b32_e32 v96, v2
	v_mov_b32_e32 v97, v2
	v_mov_b32_e32 v106, v2
	v_mov_b32_e32 v107, v2
	v_mov_b32_e32 v108, v2
	v_mov_b32_e32 v109, v2
	v_mov_b32_e32 v110, v2
	v_mov_b32_e32 v111, v2
	v_mov_b32_e32 v112, v2
	v_mov_b32_e32 v113, v2
	v_mov_b32_e32 v122, v2
	v_mov_b32_e32 v123, v2
	v_mov_b32_e32 v124, v2
	v_mov_b32_e32 v125, v2
	v_mov_b32_e32 v126, v2
	v_mov_b32_e32 v127, v2
	v_mov_b32_e32 v128, v2
	v_mov_b32_e32 v129, v2
	v_add_u32_e32 v0, 0x10000, v183
	ds_read_b128 v[134:137], v0
	ds_read_b128 v[138:141], v0 offset:1024
	ds_read_b128 v[142:145], v0 offset:2048
	ds_read_b128 v[146:149], v0 offset:3072
.LBB0_938:
	s_add_i32 s82, s52, 2
	s_add_u32 s0, s36, s50
	s_addc_u32 s1, s37, s51
	s_add_u32 s0, s0, 0x100
	s_addc_u32 s1, s1, 0
	s_add_u32 s11, s7, s50
	s_addc_u32 s83, s81, s51
	s_add_i32 s84, 0, 0x10000
	s_cmp_eq_u32 s6, s52
	s_cselect_b32 s52, s42, s0
	s_cselect_b32 s53, s43, s1
	s_cselect_b32 s85, s21, s80
	s_cselect_b32 s1, s45, s83
	s_cselect_b32 s0, s44, s11
	v_lshl_add_u64 v[188:189], v[132:133], 0, s[50:51]
	s_cselect_b32 s11, 0, s49
	s_cselect_b32 s83, s46, s48
	v_lshl_add_u64 v[188:189], v[188:189], 0, s[16:17]
	s_add_i32 m0, s66, 0xc000
	ds_read_b128 v[150:153], v210
	ds_read_b128 v[154:157], v210 offset:1024
	ds_read_b128 v[158:161], v210 offset:2048
	ds_read_b128 v[162:165], v210 offset:3072
	ds_read_b128 v[166:169], v210 offset:4096
	ds_read_b128 v[170:173], v210 offset:5120
	ds_read_b128 v[174:177], v210 offset:6144
	ds_read_b128 v[184:187], v210 offset:7168
	global_load_lds_dwordx4 v[188:189], off
	v_lshl_add_u64 v[188:189], v[130:131], 0, s[50:51]
	s_add_i32 m0, s66, 0xe000
	s_nop 0
	global_load_lds_dwordx4 v[188:189], off
	s_waitcnt lgkmcnt(8)
	s_barrier
	s_waitcnt lgkmcnt(0)
	s_setprio 1
	s_waitcnt lgkmcnt(0)
	v_mfma_f32_16x16x32_bf16 v[126:129], v[134:137], v[150:153], v[126:129]
	v_mfma_f32_16x16x32_bf16 v[122:125], v[142:145], v[150:153], v[122:125]
	v_mfma_f32_16x16x32_bf16 v[110:113], v[134:137], v[158:161], v[110:113]
	v_mfma_f32_16x16x32_bf16 v[106:109], v[142:145], v[158:161], v[106:109]
	v_mfma_f32_16x16x32_bf16 v[94:97], v[134:137], v[166:169], v[94:97]
	v_mfma_f32_16x16x32_bf16 v[90:93], v[142:145], v[166:169], v[90:93]
	v_mfma_f32_16x16x32_bf16 v[78:81], v[134:137], v[174:177], v[78:81]
	v_mfma_f32_16x16x32_bf16 v[74:77], v[142:145], v[174:177], v[74:77]
	v_mfma_f32_16x16x32_bf16 v[126:129], v[138:141], v[154:157], v[126:129]
	v_mfma_f32_16x16x32_bf16 v[122:125], v[146:149], v[154:157], v[122:125]
	v_mfma_f32_16x16x32_bf16 v[110:113], v[138:141], v[162:165], v[110:113]
	v_mfma_f32_16x16x32_bf16 v[106:109], v[146:149], v[162:165], v[106:109]
	v_mfma_f32_16x16x32_bf16 v[94:97], v[138:141], v[170:173], v[94:97]
	v_mfma_f32_16x16x32_bf16 v[90:93], v[146:149], v[170:173], v[90:93]
	v_mfma_f32_16x16x32_bf16 v[78:81], v[138:141], v[184:187], v[78:81]
	v_mfma_f32_16x16x32_bf16 v[74:77], v[146:149], v[184:187], v[74:77]
	s_setprio 0
	s_barrier
; #define PG8_LDA(dst, b, h) do { _Pragma("unroll") for (int m = 0; m < 4; ++m) _Pragma("unroll") for (int k = 0; k < 2; ++k) dst[m][k] = *(const LAS bf16x8*)(lds + PG8_SA(b, h) + aoff + m * 2048 + k * 1024); } while (0)
; #define PG8_LDB(dst, b, h) do { _Pragma("unroll") for (int n = 0; n < 2; ++n) _Pragma("unroll") for (int k = 0; k < 2; ++k) dst[n][k] = *(const LAS bf16x8*)(lds + PG8_SB(b, h) + boff + n * 2048 + k * 1024); } while (0)
; #define PG8_MMA(ai, bj, At, Bt) do { __builtin_amdgcn_s_setprio(1); _Pragma("unroll") for (int m = 0; m < 4; ++m) _Pragma("unroll") for (int n = 0; n < 2; ++n) _Pragma("unroll") for (int k = 0; k < 2; ++k) \
;         acc[ai][bj][m][n] = __builtin_amdgcn_mfma_f32_16x16x32_bf16(Bt[n][k], At[m][k], acc[ai][bj][m][n], 0, 0, 0); __builtin_amdgcn_s_setprio(0); } while (0)
; #define PG8_WAIT_V(n) asm volatile("s_waitcnt vmcnt(" #n ")" ::: "memory")
; #define PG8_WAIT_L(n) asm volatile("s_waitcnt lgkmcnt(" #n ")" ::: "memory")
; #define PG8_BAR __builtin_amdgcn_s_barrier()
; #define PG8_SCHED __builtin_amdgcn_sched_barrier(0)
; #define PG8_LDA(dst, b, h) do { _Pragma("unroll") for (int m = 0; m < 4; ++m) _Pragma("unroll") for (int k = 0; k < 2; ++k) dst[m][k] = *(const LAS bf16x8*)(lds + PG8_SA(b, h) + aoff + m * 2048 + k * 1024); } while (0)
; #define PG8_WAIT_V(n) asm volatile("s_waitcnt vmcnt(" #n ")" ::: "memory")
; #define PG8_WAIT_L(n) asm volatile("s_waitcnt lgkmcnt(" #n ")" ::: "memory")
; DI void gemm_phase_p5(LAS unsigned char* lds, const Unit u, const bf16_t* hb, const bf16_t* xn, const bf16_t* wtm, const bf16_t* wtp,
;                       char* scr, bf16_t* mixed, const float* bmerge) {
;     ...
;             PG8_WAIT_L(8); PG8_BAR; PG8_WAIT_L(0); PG8_MMA(0, 0, At, B0); PG8_BAR; PG8_SCHED;
;             PG8_LDB(B1, 0, 1); PG8_STAGE2(PG8_SB(0, 0), b2, PG8_ROWB, ldX);
;             PG8_BAR; PG8_WAIT_L(0); PG8_MMA(0, 1, At, B1); PG8_BAR;
;             PG8_LDA(At, 0, 1); PG8_STAGE2(PG8_SA(0, 0), a2, rowA, ld2);
;             PG8_BAR; PG8_WAIT_L(0); PG8_MMA(1, 0, At, B0); PG8_BAR; PG8_SCHED;
;             PG8_STAGE2(PG8_SB(0, 1), b2 + hstepB, PG8_ROWB, ldX);
;             PG8_WAIT_V(6); PG8_BAR; PG8_MMA(1, 1, At, B1); PG8_BAR;
;             PG8_LDB(B0, 1, 0); PG8_SCHED; PG8_LDA(At, 1, 0); PG8_STAGE2(PG8_SA(0, 1), a2 + hs2, rowA, ld2);
;             PG8_WAIT_L(8); PG8_BAR; PG8_WAIT_L(0); PG8_MMA(0, 0, At, B0); PG8_BAR; PG8_SCHED;
	s_add_i32 s86, 0, 0x14000
	v_lshl_add_u64 v[216:217], s[0:1], 0, v[180:181]
	s_add_i32 s0, s84, s13
	v_add_u32_e32 v0, s86, v183
	s_mov_b32 m0, s0
	ds_read_b128 v[188:191], v0
	ds_read_b128 v[192:195], v0 offset:1024
	ds_read_b128 v[196:199], v0 offset:2048
	ds_read_b128 v[212:215], v0 offset:3072
	global_load_lds_dwordx4 v[216:217], off
	v_lshl_add_u64 v[218:219], v[216:217], 0, s[24:25]
	s_add_i32 m0, s0, 0x2000
	s_nop 0
	global_load_lds_dwordx4 v[218:219], off
	s_barrier
	s_waitcnt lgkmcnt(0)
	s_setprio 1
	s_waitcnt lgkmcnt(0)
	v_mfma_f32_16x16x32_bf16 v[118:121], v[188:191], v[150:153], v[118:121]
	v_mfma_f32_16x16x32_bf16 v[114:117], v[196:199], v[150:153], v[114:117]
	v_mfma_f32_16x16x32_bf16 v[102:105], v[188:191], v[158:161], v[102:105]
	v_mfma_f32_16x16x32_bf16 v[98:101], v[196:199], v[158:161], v[98:101]
	v_mfma_f32_16x16x32_bf16 v[86:89], v[188:191], v[166:169], v[86:89]
	v_mfma_f32_16x16x32_bf16 v[82:85], v[196:199], v[166:169], v[82:85]
	v_mfma_f32_16x16x32_bf16 v[70:73], v[188:191], v[174:177], v[70:73]
	v_mfma_f32_16x16x32_bf16 v[66:69], v[196:199], v[174:177], v[66:69]
	v_mfma_f32_16x16x32_bf16 v[118:121], v[192:195], v[154:157], v[118:121]
	v_mfma_f32_16x16x32_bf16 v[114:117], v[212:215], v[154:157], v[114:117]
	v_mfma_f32_16x16x32_bf16 v[102:105], v[192:195], v[162:165], v[102:105]
	v_mfma_f32_16x16x32_bf16 v[98:101], v[212:215], v[162:165], v[98:101]
	v_mfma_f32_16x16x32_bf16 v[86:89], v[192:195], v[170:173], v[86:89]
	v_mfma_f32_16x16x32_bf16 v[82:85], v[212:215], v[170:173], v[82:85]
	v_mfma_f32_16x16x32_bf16 v[70:73], v[192:195], v[184:187], v[70:73]
	v_mfma_f32_16x16x32_bf16 v[66:69], v[212:215], v[184:187], v[66:69]
	s_setprio 0
	v_mad_u64_u32 v[218:219], s[0:1], s85, v179, v[178:179]
	s_lshl_b32 s84, s85, 6
	s_mov_b32 m0, s66
	s_add_u32 s0, s52, s84
	s_barrier
	ds_read_b128 v[150:153], v210 offset:16384
	ds_read_b128 v[154:157], v210 offset:17408
	ds_read_b128 v[158:161], v210 offset:18432
	ds_read_b128 v[162:165], v210 offset:19456
	ds_read_b128 v[166:169], v210 offset:20480
	ds_read_b128 v[170:173], v210 offset:21504
	ds_read_b128 v[174:177], v210 offset:22528
	ds_read_b128 v[184:187], v210 offset:23552
	global_load_lds_dwordx4 v218, s[52:53]
	s_addc_u32 s1, s53, 0
	s_mov_b32 m0, s67
	v_mov_b32_e32 v219, v1
	global_load_lds_dwordx4 v218, s[0:1]
	s_waitcnt vmcnt(10)
	s_barrier
	s_waitcnt lgkmcnt(0)
	v_lshl_add_u64 v[220:221], s[52:53], 0, v[218:219]
	v_lshl_add_u64 v[230:231], s[0:1], 0, v[218:219]
	s_setprio 1
	s_waitcnt lgkmcnt(0)
	v_mfma_f32_16x16x32_bf16 v[62:65], v[134:137], v[150:153], v[62:65]
	v_mfma_f32_16x16x32_bf16 v[58:61], v[142:145], v[150:153], v[58:61]
	v_mfma_f32_16x16x32_bf16 v[46:49], v[134:137], v[158:161], v[46:49]
	v_mfma_f32_16x16x32_bf16 v[42:45], v[142:145], v[158:161], v[42:45]
	v_mfma_f32_16x16x32_bf16 v[30:33], v[134:137], v[166:169], v[30:33]
	v_mfma_f32_16x16x32_bf16 v[26:29], v[142:145], v[166:169], v[26:29]
	v_mfma_f32_16x16x32_bf16 v[14:17], v[134:137], v[174:177], v[14:17]
	v_mfma_f32_16x16x32_bf16 v[10:13], v[142:145], v[174:177], v[10:13]
	v_mfma_f32_16x16x32_bf16 v[62:65], v[138:141], v[154:157], v[62:65]
	v_mfma_f32_16x16x32_bf16 v[58:61], v[146:149], v[154:157], v[58:61]
	v_mfma_f32_16x16x32_bf16 v[46:49], v[138:141], v[162:165], v[46:49]
	v_mfma_f32_16x16x32_bf16 v[42:45], v[146:149], v[162:165], v[42:45]
	v_mfma_f32_16x16x32_bf16 v[30:33], v[138:141], v[170:173], v[30:33]
	v_mfma_f32_16x16x32_bf16 v[26:29], v[146:149], v[170:173], v[26:29]
	v_mfma_f32_16x16x32_bf16 v[14:17], v[138:141], v[184:187], v[14:17]
	v_mfma_f32_16x16x32_bf16 v[10:13], v[146:149], v[184:187], v[10:13]
	s_setprio 0
	s_barrier
	s_add_i32 s0, s86, s13
	v_lshl_add_u64 v[134:135], v[216:217], 0, s[14:15]
	s_mov_b32 m0, s0
	s_nop 0
	global_load_lds_dwordx4 v[134:135], off
	v_lshl_add_u64 v[134:135], v[216:217], 0, s[26:27]
	s_add_i32 m0, s0, 0x2000
	s_nop 0
	global_load_lds_dwordx4 v[134:135], off
	v_add_u32_e32 v0, 0x18000, v183
	ds_read_b128 v[134:137], v0
	ds_read_b128 v[138:141], v0 offset:1024
	ds_read_b128 v[142:145], v0 offset:2048
	ds_read_b128 v[146:149], v0 offset:3072
	s_waitcnt vmcnt(6)
	s_barrier
	s_setprio 1
	v_mfma_f32_16x16x32_bf16 v[54:57], v[188:191], v[150:153], v[54:57]
	v_mfma_f32_16x16x32_bf16 v[50:53], v[196:199], v[150:153], v[50:53]
	v_mfma_f32_16x16x32_bf16 v[38:41], v[188:191], v[158:161], v[38:41]
	v_mfma_f32_16x16x32_bf16 v[34:37], v[196:199], v[158:161], v[34:37]
	v_mfma_f32_16x16x32_bf16 v[22:25], v[188:191], v[166:169], v[22:25]
	v_mfma_f32_16x16x32_bf16 v[18:21], v[196:199], v[166:169], v[18:21]
	v_mfma_f32_16x16x32_bf16 v[6:9], v[188:191], v[174:177], v[6:9]
	v_mfma_f32_16x16x32_bf16 v[2:5], v[196:199], v[174:177], v[2:5]
	v_mfma_f32_16x16x32_bf16 v[54:57], v[192:195], v[154:157], v[54:57]
	v_mfma_f32_16x16x32_bf16 v[50:53], v[212:215], v[154:157], v[50:53]
	v_mfma_f32_16x16x32_bf16 v[38:41], v[192:195], v[162:165], v[38:41]
	v_mfma_f32_16x16x32_bf16 v[34:37], v[212:215], v[162:165], v[34:37]
	v_mfma_f32_16x16x32_bf16 v[22:25], v[192:195], v[170:173], v[22:25]
	v_mfma_f32_16x16x32_bf16 v[18:21], v[212:215], v[170:173], v[18:21]
	v_mfma_f32_16x16x32_bf16 v[6:9], v[192:195], v[184:187], v[6:9]
	v_mfma_f32_16x16x32_bf16 v[2:5], v[212:215], v[184:187], v[2:5]
	s_setprio 0
	s_add_i32 s85, 0, 0x18000
	s_barrier
	s_add_u32 s0, s52, s83
	s_mov_b32 m0, s68
	s_addc_u32 s1, s53, s11
	ds_read_b128 v[150:153], v210 offset:32768
	ds_read_b128 v[154:157], v210 offset:33792
	ds_read_b128 v[158:161], v210 offset:34816
	ds_read_b128 v[162:165], v210 offset:35840
	ds_read_b128 v[166:169], v210 offset:36864
	ds_read_b128 v[170:173], v210 offset:37888
	ds_read_b128 v[174:177], v210 offset:38912
	ds_read_b128 v[184:187], v210 offset:39936
	global_load_lds_dwordx4 v218, s[0:1]
	s_add_u32 s0, s0, s84
	s_addc_u32 s1, s1, 0
	s_mov_b32 m0, s69
	s_nop 0
	global_load_lds_dwordx4 v218, s[0:1]
	s_waitcnt lgkmcnt(8)
	s_barrier
; #define PG8_LDA(dst, b, h) do { _Pragma("unroll") for (int m = 0; m < 4; ++m) _Pragma("unroll") for (int k = 0; k < 2; ++k) dst[m][k] = *(const LAS bf16x8*)(lds + PG8_SA(b, h) + aoff + m * 2048 + k * 1024); } while (0)
; #define PG8_LDB(dst, b, h) do { _Pragma("unroll") for (int n = 0; n < 2; ++n) _Pragma("unroll") for (int k = 0; k < 2; ++k) dst[n][k] = *(const LAS bf16x8*)(lds + PG8_SB(b, h) + boff + n * 2048 + k * 1024); } while (0)
; #define PG8_MMA(ai, bj, At, Bt) do { __builtin_amdgcn_s_setprio(1); _Pragma("unroll") for (int m = 0; m < 4; ++m) _Pragma("unroll") for (int n = 0; n < 2; ++n) _Pragma("unroll") for (int k = 0; k < 2; ++k) \
;         acc[ai][bj][m][n] = __builtin_amdgcn_mfma_f32_16x16x32_bf16(Bt[n][k], At[m][k], acc[ai][bj][m][n], 0, 0, 0); __builtin_amdgcn_s_setprio(0); } while (0)
; #define PG8_WAIT_V(n) asm volatile("s_waitcnt vmcnt(" #n ")" ::: "memory")
; #define PG8_WAIT_L(n) asm volatile("s_waitcnt lgkmcnt(" #n ")" ::: "memory")
; #define PG8_BAR __builtin_amdgcn_s_barrier()
; #define PG8_SCHED __builtin_amdgcn_sched_barrier(0)
; #define PG8_LDA(dst, b, h) do { _Pragma("unroll") for (int m = 0; m < 4; ++m) _Pragma("unroll") for (int k = 0; k < 2; ++k) dst[m][k] = *(const LAS bf16x8*)(lds + PG8_SA(b, h) + aoff + m * 2048 + k * 1024); } while (0)
; #define PG8_LDB(dst, b, h) do { _Pragma("unroll") for (int n = 0; n < 2; ++n) _Pragma("unroll") for (int k = 0; k < 2; ++k) dst[n][k] = *(const LAS bf16x8*)(lds + PG8_SB(b, h) + boff + n * 2048 + k * 1024); } while (0)
; #define PG8_WAIT_V(n) asm volatile("s_waitcnt vmcnt(" #n ")" ::: "memory")
; #define PG8_BAR __builtin_amdgcn_s_barrier()
; DI void gemm_phase_p5(LAS unsigned char* lds, const Unit u, const bf16_t* hb, const bf16_t* xn, const bf16_t* wtm, const bf16_t* wtp,
;                       char* scr, bf16_t* mixed, const float* bmerge) {
;     ...
;             PG8_WAIT_L(8); PG8_BAR; PG8_WAIT_L(0); PG8_MMA(0, 0, At, B0); PG8_BAR; PG8_SCHED;
;             PG8_LDB(B1, 1, 1); PG8_STAGE2(PG8_SB(1, 0), b3, PG8_ROWB, ldX);
;             PG8_BAR; PG8_WAIT_L(0); PG8_MMA(0, 1, At, B1); PG8_BAR;
;             PG8_LDA(At, 1, 1); PG8_STAGE2(PG8_SA(1, 0), a3, rowA, ld2);
;             PG8_BAR; PG8_WAIT_L(0); PG8_MMA(1, 0, At, B0); PG8_BAR; PG8_SCHED;
;             PG8_STAGE2(PG8_SB(1, 1), b3 + hstepB, PG8_ROWB, ldX);
;             PG8_WAIT_V(6); PG8_BAR; PG8_MMA(1, 1, At, B1); PG8_BAR;
;         }
	s_waitcnt lgkmcnt(0)
	s_setprio 1
	s_waitcnt lgkmcnt(0)
	v_mfma_f32_16x16x32_bf16 v[126:129], v[134:137], v[150:153], v[126:129]
	v_mfma_f32_16x16x32_bf16 v[122:125], v[142:145], v[150:153], v[122:125]
	v_mfma_f32_16x16x32_bf16 v[110:113], v[134:137], v[158:161], v[110:113]
	v_mfma_f32_16x16x32_bf16 v[106:109], v[142:145], v[158:161], v[106:109]
	v_mfma_f32_16x16x32_bf16 v[94:97], v[134:137], v[166:169], v[94:97]
	v_mfma_f32_16x16x32_bf16 v[90:93], v[142:145], v[166:169], v[90:93]
	v_mfma_f32_16x16x32_bf16 v[78:81], v[134:137], v[174:177], v[78:81]
	v_mfma_f32_16x16x32_bf16 v[74:77], v[142:145], v[174:177], v[74:77]
	v_mfma_f32_16x16x32_bf16 v[126:129], v[138:141], v[154:157], v[126:129]
	v_mfma_f32_16x16x32_bf16 v[122:125], v[146:149], v[154:157], v[122:125]
	v_mfma_f32_16x16x32_bf16 v[110:113], v[138:141], v[162:165], v[110:113]
	v_mfma_f32_16x16x32_bf16 v[106:109], v[146:149], v[162:165], v[106:109]
	v_mfma_f32_16x16x32_bf16 v[94:97], v[138:141], v[170:173], v[94:97]
	v_mfma_f32_16x16x32_bf16 v[90:93], v[146:149], v[170:173], v[90:93]
	v_mfma_f32_16x16x32_bf16 v[78:81], v[138:141], v[184:187], v[78:81]
	v_mfma_f32_16x16x32_bf16 v[74:77], v[146:149], v[184:187], v[74:77]
	s_setprio 0
	s_barrier
	s_add_i32 s0, 0, 0x1c000
	s_add_i32 s1, s85, s13
	v_add_u32_e32 v0, s0, v183
	v_lshl_add_u64 v[218:219], v[216:217], 0, s[16:17]
	s_mov_b32 m0, s1
	ds_read_b128 v[188:191], v0
	ds_read_b128 v[192:195], v0 offset:1024
	ds_read_b128 v[196:199], v0 offset:2048
	ds_read_b128 v[212:215], v0 offset:3072
	global_load_lds_dwordx4 v[218:219], off
	v_lshl_add_u64 v[218:219], v[216:217], 0, s[28:29]
	s_add_i32 m0, s1, 0x2000
	s_nop 0
	global_load_lds_dwordx4 v[218:219], off
	s_barrier
	s_waitcnt lgkmcnt(0)
	s_setprio 1
	s_waitcnt lgkmcnt(0)
	v_mfma_f32_16x16x32_bf16 v[118:121], v[188:191], v[150:153], v[118:121]
	v_mfma_f32_16x16x32_bf16 v[114:117], v[196:199], v[150:153], v[114:117]
	v_mfma_f32_16x16x32_bf16 v[102:105], v[188:191], v[158:161], v[102:105]
	v_mfma_f32_16x16x32_bf16 v[98:101], v[196:199], v[158:161], v[98:101]
	v_mfma_f32_16x16x32_bf16 v[86:89], v[188:191], v[166:169], v[86:89]
	v_mfma_f32_16x16x32_bf16 v[82:85], v[196:199], v[166:169], v[82:85]
	v_mfma_f32_16x16x32_bf16 v[70:73], v[188:191], v[174:177], v[70:73]
	v_mfma_f32_16x16x32_bf16 v[66:69], v[196:199], v[174:177], v[66:69]
	v_mfma_f32_16x16x32_bf16 v[118:121], v[192:195], v[154:157], v[118:121]
	v_mfma_f32_16x16x32_bf16 v[114:117], v[212:215], v[154:157], v[114:117]
	v_mfma_f32_16x16x32_bf16 v[102:105], v[192:195], v[162:165], v[102:105]
	v_mfma_f32_16x16x32_bf16 v[98:101], v[212:215], v[162:165], v[98:101]
	v_mfma_f32_16x16x32_bf16 v[86:89], v[192:195], v[170:173], v[86:89]
	v_mfma_f32_16x16x32_bf16 v[82:85], v[212:215], v[170:173], v[82:85]
	v_mfma_f32_16x16x32_bf16 v[70:73], v[192:195], v[184:187], v[70:73]
	v_mfma_f32_16x16x32_bf16 v[66:69], v[212:215], v[184:187], v[66:69]
	s_setprio 0
	s_mov_b32 m0, s72
	v_lshl_add_u64 v[218:219], v[220:221], 0, s[16:17]
	s_barrier
	ds_read_b128 v[150:153], v210 offset:49152
	ds_read_b128 v[154:157], v210 offset:50176
	ds_read_b128 v[158:161], v210 offset:51200
	ds_read_b128 v[162:165], v210 offset:52224
	ds_read_b128 v[166:169], v210 offset:53248
	ds_read_b128 v[170:173], v210 offset:54272
	ds_read_b128 v[174:177], v210 offset:55296
	ds_read_b128 v[184:187], v210 offset:56320
	global_load_lds_dwordx4 v[218:219], off
	v_lshl_add_u64 v[218:219], v[230:231], 0, s[16:17]
	s_mov_b32 m0, s73
	s_nop 0
	global_load_lds_dwordx4 v[218:219], off
	s_waitcnt vmcnt(10)
	s_barrier
	s_waitcnt lgkmcnt(0)
	s_setprio 1
	s_waitcnt lgkmcnt(0)
	v_mfma_f32_16x16x32_bf16 v[62:65], v[134:137], v[150:153], v[62:65]
	v_mfma_f32_16x16x32_bf16 v[58:61], v[142:145], v[150:153], v[58:61]
	v_mfma_f32_16x16x32_bf16 v[46:49], v[134:137], v[158:161], v[46:49]
	v_mfma_f32_16x16x32_bf16 v[42:45], v[142:145], v[158:161], v[42:45]
	v_mfma_f32_16x16x32_bf16 v[30:33], v[134:137], v[166:169], v[30:33]
	v_mfma_f32_16x16x32_bf16 v[26:29], v[142:145], v[166:169], v[26:29]
	v_mfma_f32_16x16x32_bf16 v[14:17], v[134:137], v[174:177], v[14:17]
	v_mfma_f32_16x16x32_bf16 v[10:13], v[142:145], v[174:177], v[10:13]
	v_mfma_f32_16x16x32_bf16 v[62:65], v[138:141], v[154:157], v[62:65]
	v_mfma_f32_16x16x32_bf16 v[58:61], v[146:149], v[154:157], v[58:61]
	v_mfma_f32_16x16x32_bf16 v[46:49], v[138:141], v[162:165], v[46:49]
	v_mfma_f32_16x16x32_bf16 v[42:45], v[146:149], v[162:165], v[42:45]
	v_mfma_f32_16x16x32_bf16 v[30:33], v[138:141], v[170:173], v[30:33]
	v_mfma_f32_16x16x32_bf16 v[26:29], v[146:149], v[170:173], v[26:29]
	v_mfma_f32_16x16x32_bf16 v[14:17], v[138:141], v[184:187], v[14:17]
	v_mfma_f32_16x16x32_bf16 v[10:13], v[146:149], v[184:187], v[10:13]
	s_setprio 0
	s_barrier
	s_add_i32 s0, s0, s13
	v_lshl_add_u64 v[134:135], v[216:217], 0, s[18:19]
	s_mov_b32 m0, s0
	s_nop 0
	global_load_lds_dwordx4 v[134:135], off
	v_lshl_add_u64 v[134:135], v[216:217], 0, s[30:31]
	s_add_i32 m0, s0, 0x2000
	s_nop 0
	global_load_lds_dwordx4 v[134:135], off
	v_add_u32_e32 v0, 0x10000, v183
	ds_read_b128 v[134:137], v0
	ds_read_b128 v[138:141], v0 offset:1024
	ds_read_b128 v[142:145], v0 offset:2048
	ds_read_b128 v[146:149], v0 offset:3072
	s_waitcnt vmcnt(6)
	s_barrier
; DI int tidx() { int t = threadIdx.x; asm volatile("" : "+v"(t)); return t; }
; #define PG8_MMA(ai, bj, At, Bt) do { __builtin_amdgcn_s_setprio(1); _Pragma("unroll") for (int m = 0; m < 4; ++m) _Pragma("unroll") for (int n = 0; n < 2; ++n) _Pragma("unroll") for (int k = 0; k < 2; ++k) \
;         acc[ai][bj][m][n] = __builtin_amdgcn_mfma_f32_16x16x32_bf16(Bt[n][k], At[m][k], acc[ai][bj][m][n], 0, 0, 0); __builtin_amdgcn_s_setprio(0); } while (0)
; #define PG8_WAIT_V(n) asm volatile("s_waitcnt vmcnt(" #n ")" ::: "memory")
; #define PG8_BAR __builtin_amdgcn_s_barrier()
; #define PG8_MMA(ai, bj, At, Bt) do { __builtin_amdgcn_s_setprio(1); _Pragma("unroll") for (int m = 0; m < 4; ++m) _Pragma("unroll") for (int n = 0; n < 2; ++n) _Pragma("unroll") for (int k = 0; k < 2; ++k)         acc[ai][bj][m][n] = __builtin_amdgcn_mfma_f32_16x16x32_bf16(Bt[n][k], At[m][k], acc[ai][bj][m][n], 0, 0, 0); __builtin_amdgcn_s_setprio(0); } while (0)
; #define PG8_WAIT_V(n) asm volatile("s_waitcnt vmcnt(" #n ")" ::: "memory")
; #define PG8_BAR __builtin_amdgcn_s_barrier()
;   DI void operator()(const f32x4 (&acc)[2][2][4][2], const Unit&, int, int, int, int) const {
;     char* sb = scr; asm volatile("" : "+s"(sb));
;     const unsigned toff = (unsigned)tidx() * 16u;
; #pragma unroll
;     for (int ai = 0; ai < 2; ++ai)
; #pragma unroll
;       for (int m = 0; m < 4; ++m)
; #pragma unroll
;         for (int bj = 0; bj < 2; ++bj) *(u32x4*)(sb + (size_t)(((ai * 4 + m) * 2 + bj) * 8192) + toff) = pack8(acc[ai][bj][m][0], acc[ai][bj][m][1]);
;   }
; DI void gemm_phase_p5(LAS unsigned char* lds, const Unit u, const bf16_t* hb, const bf16_t* xn, const bf16_t* wtm, const bf16_t* wtp,
;                       char* scr, bf16_t* mixed, const float* bmerge) {
;     ...
;             PG8_WAIT_V(6); PG8_BAR; PG8_MMA(1, 1, At, B1); PG8_BAR;
;         }
	s_setprio 1
	v_mfma_f32_16x16x32_bf16 v[54:57], v[188:191], v[150:153], v[54:57]
	v_mfma_f32_16x16x32_bf16 v[50:53], v[196:199], v[150:153], v[50:53]
	v_mfma_f32_16x16x32_bf16 v[38:41], v[188:191], v[158:161], v[38:41]
	v_mfma_f32_16x16x32_bf16 v[34:37], v[196:199], v[158:161], v[34:37]
	v_mfma_f32_16x16x32_bf16 v[22:25], v[188:191], v[166:169], v[22:25]
	v_mfma_f32_16x16x32_bf16 v[18:21], v[196:199], v[166:169], v[18:21]
	v_mfma_f32_16x16x32_bf16 v[6:9], v[188:191], v[174:177], v[6:9]
	v_mfma_f32_16x16x32_bf16 v[2:5], v[196:199], v[174:177], v[2:5]
	v_mfma_f32_16x16x32_bf16 v[54:57], v[192:195], v[154:157], v[54:57]
	v_mfma_f32_16x16x32_bf16 v[50:53], v[212:215], v[154:157], v[50:53]
	v_mfma_f32_16x16x32_bf16 v[38:41], v[192:195], v[162:165], v[38:41]
	v_mfma_f32_16x16x32_bf16 v[34:37], v[212:215], v[162:165], v[34:37]
	v_mfma_f32_16x16x32_bf16 v[22:25], v[192:195], v[170:173], v[22:25]
	v_mfma_f32_16x16x32_bf16 v[18:21], v[212:215], v[170:173], v[18:21]
	v_mfma_f32_16x16x32_bf16 v[6:9], v[192:195], v[184:187], v[6:9]
	v_mfma_f32_16x16x32_bf16 v[2:5], v[212:215], v[184:187], v[2:5]
	s_setprio 0
	s_add_u32 s50, s50, 0x100
	s_addc_u32 s51, s51, 0
	s_cmp_ge_i32 s82, s10
	s_mov_b32 s52, s82
	s_barrier
	s_cbranch_scc0 .LBB0_938
	s_waitcnt lgkmcnt(0)
	v_mov_b32_e32 v138, v201
	s_cmp_lg_u32 s79, 0
	s_cbranch_scc0 .LBB0_941
	s_mov_b64 s[0:1], s[8:9]
	v_mov_b32_e32 v0, v201
	v_cvt_pk_bf16_f32 v130, v126, v127
	v_lshlrev_b32_e32 v0, 4, v0
	v_lshl_add_u64 v[134:135], s[0:1], 0, v[0:1]
	s_movk_i32 s0, 0x2000
	v_cvt_pk_bf16_f32 v131, v128, v129
	v_cvt_pk_bf16_f32 v132, v122, v123
	v_cvt_pk_bf16_f32 v133, v124, v125
	v_add_co_u32_e32 v136, vcc, s0, v134
	flat_store_dwordx4 v[134:135], v[130:133]
	s_nop 0
	v_addc_co_u32_e32 v137, vcc, 0, v135, vcc
	v_cvt_pk_bf16_f32 v130, v118, v119
	v_cvt_pk_bf16_f32 v131, v120, v121
	v_cvt_pk_bf16_f32 v132, v114, v115
	v_cvt_pk_bf16_f32 v133, v116, v117
	s_movk_i32 s0, 0x4000
	flat_store_dwordx4 v[136:137], v[130:133]
	v_add_co_u32_e32 v136, vcc, s0, v134
	s_nop 0
	v_cvt_pk_bf16_f32 v130, v110, v111
	v_cvt_pk_bf16_f32 v131, v112, v113
	v_cvt_pk_bf16_f32 v132, v106, v107
	v_cvt_pk_bf16_f32 v133, v108, v109
	v_addc_co_u32_e32 v137, vcc, 0, v135, vcc
	s_movk_i32 s0, 0x6000
	flat_store_dwordx4 v[136:137], v[130:133]
	v_add_co_u32_e32 v136, vcc, s0, v134
	s_nop 0
	v_cvt_pk_bf16_f32 v130, v102, v103
	v_cvt_pk_bf16_f32 v131, v104, v105
	v_cvt_pk_bf16_f32 v132, v98, v99
	v_cvt_pk_bf16_f32 v133, v100, v101
	v_addc_co_u32_e32 v137, vcc, 0, v135, vcc
	s_mov_b32 s0, 0x8000
	flat_store_dwordx4 v[136:137], v[130:133]
	v_add_co_u32_e32 v136, vcc, s0, v134
	s_nop 0
	v_cvt_pk_bf16_f32 v130, v94, v95
	v_cvt_pk_bf16_f32 v131, v96, v97
	v_cvt_pk_bf16_f32 v132, v90, v91
	v_cvt_pk_bf16_f32 v133, v92, v93
	v_addc_co_u32_e32 v137, vcc, 0, v135, vcc
	s_mov_b32 s0, 0xa000
	flat_store_dwordx4 v[136:137], v[130:133]
	v_add_co_u32_e32 v136, vcc, s0, v134
	s_nop 0
	v_cvt_pk_bf16_f32 v130, v86, v87
	v_cvt_pk_bf16_f32 v131, v88, v89
	v_cvt_pk_bf16_f32 v132, v82, v83
	v_cvt_pk_bf16_f32 v133, v84, v85
	v_addc_co_u32_e32 v137, vcc, 0, v135, vcc
	s_mov_b32 s0, 0xc000
	flat_store_dwordx4 v[136:137], v[130:133]
	v_add_co_u32_e32 v136, vcc, s0, v134
	s_nop 0
	v_cvt_pk_bf16_f32 v130, v78, v79
	v_cvt_pk_bf16_f32 v131, v80, v81
	v_cvt_pk_bf16_f32 v132, v74, v75
	v_cvt_pk_bf16_f32 v133, v76, v77
	v_addc_co_u32_e32 v137, vcc, 0, v135, vcc
	s_mov_b32 s0, 0xe000
	flat_store_dwordx4 v[136:137], v[130:133]
	v_add_co_u32_e32 v136, vcc, s0, v134
	s_nop 0
	v_cvt_pk_bf16_f32 v130, v70, v71
	v_cvt_pk_bf16_f32 v131, v72, v73
	v_cvt_pk_bf16_f32 v132, v66, v67
	v_cvt_pk_bf16_f32 v133, v68, v69
	v_addc_co_u32_e32 v137, vcc, 0, v135, vcc
	s_mov_b32 s0, 0x10000
	flat_store_dwordx4 v[136:137], v[130:133]
	v_add_co_u32_e32 v136, vcc, s0, v134
	s_nop 0
	v_cvt_pk_bf16_f32 v130, v62, v63
	v_cvt_pk_bf16_f32 v131, v64, v65
	v_cvt_pk_bf16_f32 v132, v58, v59
	v_cvt_pk_bf16_f32 v133, v60, v61
	v_addc_co_u32_e32 v137, vcc, 0, v135, vcc
	s_mov_b32 s0, 0x12000
	flat_store_dwordx4 v[136:137], v[130:133]
	v_add_co_u32_e32 v136, vcc, s0, v134
	s_nop 0
	v_cvt_pk_bf16_f32 v130, v54, v55
	v_cvt_pk_bf16_f32 v131, v56, v57
	v_cvt_pk_bf16_f32 v132, v50, v51
	v_cvt_pk_bf16_f32 v133, v52, v53
	v_addc_co_u32_e32 v137, vcc, 0, v135, vcc
	s_mov_b32 s0, 0x14000
	flat_store_dwordx4 v[136:137], v[130:133]
	v_add_co_u32_e32 v136, vcc, s0, v134
	s_nop 0
	v_cvt_pk_bf16_f32 v130, v46, v47
	v_cvt_pk_bf16_f32 v131, v48, v49
	v_cvt_pk_bf16_f32 v132, v42, v43
	v_cvt_pk_bf16_f32 v133, v44, v45
	v_addc_co_u32_e32 v137, vcc, 0, v135, vcc
	s_mov_b32 s0, 0x16000
	flat_store_dwordx4 v[136:137], v[130:133]
	v_add_co_u32_e32 v136, vcc, s0, v134
	s_nop 0
	v_cvt_pk_bf16_f32 v130, v38, v39
	v_cvt_pk_bf16_f32 v131, v40, v41
	v_cvt_pk_bf16_f32 v132, v34, v35
	v_cvt_pk_bf16_f32 v133, v36, v37
	v_addc_co_u32_e32 v137, vcc, 0, v135, vcc
	s_mov_b32 s0, 0x18000
	flat_store_dwordx4 v[136:137], v[130:133]
	v_add_co_u32_e32 v136, vcc, s0, v134
	s_nop 0
	v_cvt_pk_bf16_f32 v130, v30, v31
	v_cvt_pk_bf16_f32 v131, v32, v33
	v_cvt_pk_bf16_f32 v132, v26, v27
	v_cvt_pk_bf16_f32 v133, v28, v29
	v_addc_co_u32_e32 v137, vcc, 0, v135, vcc
	s_mov_b32 s0, 0x1a000
	flat_store_dwordx4 v[136:137], v[130:133]
	v_add_co_u32_e32 v136, vcc, s0, v134
	s_nop 0
	v_cvt_pk_bf16_f32 v130, v22, v23
	v_cvt_pk_bf16_f32 v131, v24, v25
	v_cvt_pk_bf16_f32 v132, v18, v19
	v_cvt_pk_bf16_f32 v133, v20, v21
	v_addc_co_u32_e32 v137, vcc, 0, v135, vcc
	s_mov_b32 s0, 0x1c000
	flat_store_dwordx4 v[136:137], v[130:133]
	v_add_co_u32_e32 v136, vcc, s0, v134
	s_nop 0
	v_cvt_pk_bf16_f32 v130, v14, v15
	v_addc_co_u32_e32 v137, vcc, 0, v135, vcc
	v_cvt_pk_bf16_f32 v131, v16, v17
	v_cvt_pk_bf16_f32 v132, v10, v11
	v_cvt_pk_bf16_f32 v133, v12, v13
	v_add_co_u32_e32 v134, vcc, 0x1e000, v134
	flat_store_dwordx4 v[136:137], v[130:133]
	s_nop 0
	v_addc_co_u32_e32 v135, vcc, 0, v135, vcc
	v_cvt_pk_bf16_f32 v130, v6, v7
	v_cvt_pk_bf16_f32 v131, v8, v9
	v_cvt_pk_bf16_f32 v132, v2, v3
	v_cvt_pk_bf16_f32 v133, v4, v5
	flat_store_dwordx4 v[134:135], v[130:133]
	s_cbranch_execnz .LBB0_930
	s_branch .LBB0_942

; #define PG8_STAGE(bufoff, gbase, voff) do { _Pragma("unroll") for (int _i = 0; _i < 2; ++_i) \
;         __builtin_amdgcn_global_load_lds((const unsigned*)((const char*)(gbase) + (voff)[_i]), (LAS unsigned*)(lds + (bufoff) + ldsw + _i * 8192), 16, 0, 0); } while (0)
; #define PG8_LDA(dst, b, h) do { _Pragma("unroll") for (int m = 0; m < 4; ++m) _Pragma("unroll") for (int k = 0; k < 2; ++k) dst[m][k] = *(const LAS bf16x8*)(lds + PG8_SA(b, h) + aoff + m * 2048 + k * 1024); } while (0)
; #define PG8_LDB(dst, b, h) do { _Pragma("unroll") for (int n = 0; n < 2; ++n) _Pragma("unroll") for (int k = 0; k < 2; ++k) dst[n][k] = *(const LAS bf16x8*)(lds + PG8_SB(b, h) + boff + n * 2048 + k * 1024); } while (0)
; #define PG8_MMA(ai, bj, At, Bt) do { __builtin_amdgcn_s_setprio(1); _Pragma("unroll") for (int m = 0; m < 4; ++m) _Pragma("unroll") for (int n = 0; n < 2; ++n) _Pragma("unroll") for (int k = 0; k < 2; ++k) \
;         acc[ai][bj][m][n] = __builtin_amdgcn_mfma_f32_16x16x32_bf16(Bt[n][k], At[m][k], acc[ai][bj][m][n], 0, 0, 0); __builtin_amdgcn_s_setprio(0); } while (0)
; #define PG8_WAIT_L(n) asm volatile("s_waitcnt lgkmcnt(" #n ")" ::: "memory")
; #define PG8_BAR __builtin_amdgcn_s_barrier()
; #define PG8_SCHED __builtin_amdgcn_sched_barrier(0)
; #define PG8_WAIT_L(n) asm volatile("s_waitcnt lgkmcnt(" #n ")" ::: "memory")
; #define PG8_BAR __builtin_amdgcn_s_barrier()
; #define PG8_SCHED __builtin_amdgcn_sched_barrier(0)
; template <class Epi, class Sched>
; DI void gemm_phase(LAS unsigned char* lds, const Gemm g, const Sched& S, const Epi& E) {
;     ...
;         const bool has_next = S.next(ui + 1, nxt);
;         const char* nA = has_next ? (const char*)g.A + (size_t)nxt.pm * tstepA : cA; const char* nB = has_next ? (const char*)g.Bt + (size_t)nxt.pn * tstepB : cB;
;         for (int t = 0; t < nt; t += 2) {
;             const bool last = (t == nt - 2);
;             const char* a1 = cA + (size_t)(t + 1) * kstep;
;             const char* a2 = last ? nA : cA + (size_t)(t + 2) * kstep; const char* b2 = last ? nB : cB + (size_t)(t + 2) * kstep;
;             const char* a3 = a2 + kstep; const char* b3 = b2 + kstep;
;             if (last && has_next) S.a_ready(nxt);
;             PG8_LDB(B0, 0, 0); PG8_SCHED; PG8_LDA(At, 0, 0); PG8_STAGE(PG8_SA(1, 1), a1 + hstepA, voffA);
;             PG8_WAIT_L(8); PG8_BAR; PG8_WAIT_L(0); PG8_MMA(0, 0, At, B0); PG8_BAR; PG8_SCHED;
.LBB0_1038:
	s_ashr_i32 s13, s12, 31
	s_lshl_b64 s[0:1], s[12:13], 19
	s_add_u32 s34, s48, s0
	v_cmp_lt_i64_e32 vcc, s[6:7], v[206:207]
	s_addc_u32 s35, s49, s1
	s_and_b64 s[0:1], vcc, exec
	s_cselect_b32 s6, s35, s45
	s_cselect_b32 s7, s34, s44
	s_ashr_i32 s9, s8, 31
	s_lshl_b64 s[0:1], s[8:9], 19
	s_add_u32 s38, s22, s0
	s_addc_u32 s39, s23, s1
	s_and_b64 s[0:1], vcc, exec
	s_cselect_b32 s9, s39, s43
	s_cselect_b32 s13, s38, s42
	s_add_u32 s58, s42, 0x100
	s_addc_u32 s59, s43, 0
	s_add_u32 s42, s44, 0x40080
	v_mov_b32_e32 v2, 0
	s_addc_u32 s43, s45, 0
	s_mov_b32 s60, -2
	v_mov_b32_e32 v3, v2
	v_mov_b32_e32 v4, v2
	v_mov_b32_e32 v5, v2
	v_mov_b32_e32 v6, v2
	v_mov_b32_e32 v7, v2
	v_mov_b32_e32 v8, v2
	v_mov_b32_e32 v9, v2
	v_mov_b32_e32 v10, v2
	v_mov_b32_e32 v11, v2
	v_mov_b32_e32 v12, v2
	v_mov_b32_e32 v13, v2
	v_mov_b32_e32 v14, v2
	v_mov_b32_e32 v15, v2
	v_mov_b32_e32 v16, v2
	v_mov_b32_e32 v17, v2
	v_mov_b32_e32 v34, v2
	v_mov_b32_e32 v35, v2
	v_mov_b32_e32 v36, v2
	v_mov_b32_e32 v37, v2
	v_mov_b32_e32 v38, v2
	v_mov_b32_e32 v39, v2
	v_mov_b32_e32 v40, v2
	v_mov_b32_e32 v41, v2
	v_mov_b32_e32 v42, v2
	v_mov_b32_e32 v43, v2
	v_mov_b32_e32 v44, v2
	v_mov_b32_e32 v45, v2
	v_mov_b32_e32 v46, v2
	v_mov_b32_e32 v47, v2
	v_mov_b32_e32 v48, v2
	v_mov_b32_e32 v49, v2
	v_mov_b32_e32 v18, v2
	v_mov_b32_e32 v19, v2
	v_mov_b32_e32 v20, v2
	v_mov_b32_e32 v21, v2
	v_mov_b32_e32 v22, v2
	v_mov_b32_e32 v23, v2
	v_mov_b32_e32 v24, v2
	v_mov_b32_e32 v25, v2
	v_mov_b32_e32 v26, v2
	v_mov_b32_e32 v27, v2
	v_mov_b32_e32 v28, v2
	v_mov_b32_e32 v29, v2
	v_mov_b32_e32 v30, v2
	v_mov_b32_e32 v31, v2
	v_mov_b32_e32 v32, v2
	v_mov_b32_e32 v33, v2
	v_mov_b32_e32 v50, v2
	v_mov_b32_e32 v51, v2
	v_mov_b32_e32 v52, v2
	v_mov_b32_e32 v53, v2
	v_mov_b32_e32 v54, v2
	v_mov_b32_e32 v55, v2
	v_mov_b32_e32 v56, v2
	v_mov_b32_e32 v57, v2
	v_mov_b32_e32 v58, v2
	v_mov_b32_e32 v59, v2
	v_mov_b32_e32 v60, v2
	v_mov_b32_e32 v61, v2
	v_mov_b32_e32 v62, v2
	v_mov_b32_e32 v63, v2
	v_mov_b32_e32 v64, v2
	v_mov_b32_e32 v65, v2
	v_mov_b32_e32 v66, v2
	v_mov_b32_e32 v67, v2
	v_mov_b32_e32 v68, v2
	v_mov_b32_e32 v69, v2
	v_mov_b32_e32 v70, v2
	v_mov_b32_e32 v71, v2
	v_mov_b32_e32 v72, v2
	v_mov_b32_e32 v73, v2
	v_mov_b32_e32 v74, v2
	v_mov_b32_e32 v75, v2
	v_mov_b32_e32 v76, v2
	v_mov_b32_e32 v77, v2
	v_mov_b32_e32 v78, v2
	v_mov_b32_e32 v79, v2
	v_mov_b32_e32 v80, v2
	v_mov_b32_e32 v81, v2
	v_mov_b32_e32 v98, v2
	v_mov_b32_e32 v99, v2
	v_mov_b32_e32 v100, v2
	v_mov_b32_e32 v101, v2
	v_mov_b32_e32 v102, v2
	v_mov_b32_e32 v103, v2
	v_mov_b32_e32 v104, v2
	v_mov_b32_e32 v105, v2
	v_mov_b32_e32 v106, v2
	v_mov_b32_e32 v107, v2
	v_mov_b32_e32 v108, v2
	v_mov_b32_e32 v109, v2
	v_mov_b32_e32 v110, v2
	v_mov_b32_e32 v111, v2
	v_mov_b32_e32 v112, v2
	v_mov_b32_e32 v113, v2
	v_mov_b32_e32 v82, v2
	v_mov_b32_e32 v83, v2
	v_mov_b32_e32 v84, v2
	v_mov_b32_e32 v85, v2
	v_mov_b32_e32 v86, v2
	v_mov_b32_e32 v87, v2
	v_mov_b32_e32 v88, v2
	v_mov_b32_e32 v89, v2
	v_mov_b32_e32 v90, v2
	v_mov_b32_e32 v91, v2
	v_mov_b32_e32 v92, v2
	v_mov_b32_e32 v93, v2
	v_mov_b32_e32 v94, v2
	v_mov_b32_e32 v95, v2
	v_mov_b32_e32 v96, v2
	v_mov_b32_e32 v97, v2
	v_mov_b32_e32 v114, v2
	v_mov_b32_e32 v115, v2
	v_mov_b32_e32 v116, v2
	v_mov_b32_e32 v117, v2
	v_mov_b32_e32 v118, v2
	v_mov_b32_e32 v119, v2
	v_mov_b32_e32 v120, v2
	v_mov_b32_e32 v121, v2
	v_mov_b32_e32 v122, v2
	v_mov_b32_e32 v123, v2
	v_mov_b32_e32 v124, v2
	v_mov_b32_e32 v125, v2
	v_mov_b32_e32 v126, v2
	v_mov_b32_e32 v127, v2
	v_mov_b32_e32 v128, v2
	v_mov_b32_e32 v129, v2
	v_add_u32_e32 v152, 0x10000, v145
	ds_read_b128 v[136:139], v152
	ds_read_b128 v[140:143], v152 offset:1024
	ds_read_b128 v[148:151], v152 offset:2048
	ds_read_b128 v[152:155], v152 offset:3072
.LBB0_1039:
	s_add_u32 s0, s42, 0xfffc0080
	s_addc_u32 s1, s43, -1
	s_add_i32 s11, 0, 0x10000
	s_cmp_eq_u32 s60, 12
	s_cselect_b32 s47, s6, s1
	s_cselect_b32 s46, s7, s0
	s_cselect_b32 s45, s9, s59
	s_cselect_b32 s44, s13, s58
	v_lshl_add_u64 v[188:189], s[42:43], 0, v[134:135]
	s_add_i32 m0, s51, 0xc000
	ds_read_b128 v[156:159], v147
	ds_read_b128 v[160:163], v147 offset:1024
	ds_read_b128 v[164:167], v147 offset:2048
	ds_read_b128 v[168:171], v147 offset:3072
	ds_read_b128 v[172:175], v147 offset:4096
	ds_read_b128 v[176:179], v147 offset:5120
	ds_read_b128 v[180:183], v147 offset:6144
	ds_read_b128 v[184:187], v147 offset:7168
	global_load_lds_dwordx4 v[188:189], off
	v_lshl_add_u64 v[188:189], s[42:43], 0, v[132:133]
	s_add_i32 m0, s51, 0xe000
	s_nop 0
	global_load_lds_dwordx4 v[188:189], off
	s_waitcnt lgkmcnt(8)
	s_barrier
	s_waitcnt lgkmcnt(0)
	s_setprio 1
	s_waitcnt lgkmcnt(0)
	v_mfma_f32_16x16x32_bf16 v[126:129], v[136:139], v[156:159], v[126:129]
	v_mfma_f32_16x16x32_bf16 v[122:125], v[148:151], v[156:159], v[122:125]
	v_mfma_f32_16x16x32_bf16 v[118:121], v[136:139], v[164:167], v[118:121]
	v_mfma_f32_16x16x32_bf16 v[114:117], v[148:151], v[164:167], v[114:117]
	v_mfma_f32_16x16x32_bf16 v[94:97], v[136:139], v[172:175], v[94:97]
	v_mfma_f32_16x16x32_bf16 v[90:93], v[148:151], v[172:175], v[90:93]
	v_mfma_f32_16x16x32_bf16 v[86:89], v[136:139], v[180:183], v[86:89]
	v_mfma_f32_16x16x32_bf16 v[82:85], v[148:151], v[180:183], v[82:85]
	v_mfma_f32_16x16x32_bf16 v[126:129], v[140:143], v[160:163], v[126:129]
	v_mfma_f32_16x16x32_bf16 v[122:125], v[152:155], v[160:163], v[122:125]
	v_mfma_f32_16x16x32_bf16 v[118:121], v[140:143], v[168:171], v[118:121]
	v_mfma_f32_16x16x32_bf16 v[114:117], v[152:155], v[168:171], v[114:117]
	v_mfma_f32_16x16x32_bf16 v[94:97], v[140:143], v[176:179], v[94:97]
	v_mfma_f32_16x16x32_bf16 v[90:93], v[152:155], v[176:179], v[90:93]
	v_mfma_f32_16x16x32_bf16 v[86:89], v[140:143], v[184:187], v[86:89]
	v_mfma_f32_16x16x32_bf16 v[82:85], v[152:155], v[184:187], v[82:85]
	s_setprio 0
	s_barrier
; #define PG8_STAGE(bufoff, gbase, voff) do { _Pragma("unroll") for (int _i = 0; _i < 2; ++_i) \
;         __builtin_amdgcn_global_load_lds((const unsigned*)((const char*)(gbase) + (voff)[_i]), (LAS unsigned*)(lds + (bufoff) + ldsw + _i * 8192), 16, 0, 0); } while (0)
; #define PG8_LDA(dst, b, h) do { _Pragma("unroll") for (int m = 0; m < 4; ++m) _Pragma("unroll") for (int k = 0; k < 2; ++k) dst[m][k] = *(const LAS bf16x8*)(lds + PG8_SA(b, h) + aoff + m * 2048 + k * 1024); } while (0)
; #define PG8_LDB(dst, b, h) do { _Pragma("unroll") for (int n = 0; n < 2; ++n) _Pragma("unroll") for (int k = 0; k < 2; ++k) dst[n][k] = *(const LAS bf16x8*)(lds + PG8_SB(b, h) + boff + n * 2048 + k * 1024); } while (0)
; #define PG8_MMA(ai, bj, At, Bt) do { __builtin_amdgcn_s_setprio(1); _Pragma("unroll") for (int m = 0; m < 4; ++m) _Pragma("unroll") for (int n = 0; n < 2; ++n) _Pragma("unroll") for (int k = 0; k < 2; ++k) \
;         acc[ai][bj][m][n] = __builtin_amdgcn_mfma_f32_16x16x32_bf16(Bt[n][k], At[m][k], acc[ai][bj][m][n], 0, 0, 0); __builtin_amdgcn_s_setprio(0); } while (0)
; #define PG8_WAIT_V(n) asm volatile("s_waitcnt vmcnt(" #n ")" ::: "memory")
; #define PG8_WAIT_L(n) asm volatile("s_waitcnt lgkmcnt(" #n ")" ::: "memory")
; #define PG8_BAR __builtin_amdgcn_s_barrier()
; #define PG8_SCHED __builtin_amdgcn_sched_barrier(0)
; #define PG8_WAIT_V(n) asm volatile("s_waitcnt vmcnt(" #n ")" ::: "memory")
; #define PG8_WAIT_L(n) asm volatile("s_waitcnt lgkmcnt(" #n ")" ::: "memory")
; #define PG8_BAR __builtin_amdgcn_s_barrier()
; template <class Epi, class Sched>
; DI void gemm_phase(LAS unsigned char* lds, const Gemm g, const Sched& S, const Epi& E) {
;     ...
;             PG8_WAIT_L(8); PG8_BAR; PG8_WAIT_L(0); PG8_MMA(0, 0, At, B0); PG8_BAR; PG8_SCHED;
;             PG8_LDB(B1, 0, 1); PG8_STAGE(PG8_SB(0, 0), b2, voffB);
;             PG8_BAR; PG8_WAIT_L(0); PG8_MMA(0, 1, At, B1); PG8_BAR;
;             PG8_LDA(At, 0, 1); PG8_STAGE(PG8_SA(0, 0), a2, voffA);
;             PG8_BAR; PG8_WAIT_L(0); PG8_MMA(1, 0, At, B0); PG8_BAR; PG8_SCHED;
;             PG8_STAGE(PG8_SB(0, 1), b2 + hstepB, voffB);
;             PG8_WAIT_V(6); PG8_BAR; PG8_MMA(1, 1, At, B1); PG8_BAR;
;             PG8_LDB(B0, 1, 0); PG8_SCHED; PG8_LDA(At, 1, 0); PG8_STAGE(PG8_SA(0, 1), a2 + hstepA, voffA);
;             PG8_WAIT_L(8); PG8_BAR; PG8_WAIT_L(0); PG8_MMA(0, 0, At, B0); PG8_BAR; PG8_SCHED;
	s_add_i32 s61, 0, 0x14000
	s_add_i32 s0, s11, s50
	v_add_u32_e32 v210, s61, v145
	v_lshl_add_u64 v[214:215], s[44:45], 0, v[0:1]
	s_mov_b32 m0, s0
	ds_read_b128 v[188:191], v210
	ds_read_b128 v[192:195], v210 offset:1024
	ds_read_b128 v[196:199], v210 offset:2048
	ds_read_b128 v[210:213], v210 offset:3072
	global_load_lds_dwordx4 v[214:215], off
	v_lshl_add_u64 v[216:217], s[44:45], 0, v[130:131]
	s_add_i32 m0, s0, 0x2000
	s_nop 0
	global_load_lds_dwordx4 v[216:217], off
	s_barrier
	s_waitcnt lgkmcnt(0)
	s_setprio 1
	s_waitcnt lgkmcnt(0)
	v_mfma_f32_16x16x32_bf16 v[110:113], v[188:191], v[156:159], v[110:113]
	v_mfma_f32_16x16x32_bf16 v[106:109], v[196:199], v[156:159], v[106:109]
	v_mfma_f32_16x16x32_bf16 v[102:105], v[188:191], v[164:167], v[102:105]
	v_mfma_f32_16x16x32_bf16 v[98:101], v[196:199], v[164:167], v[98:101]
	v_mfma_f32_16x16x32_bf16 v[78:81], v[188:191], v[172:175], v[78:81]
	v_mfma_f32_16x16x32_bf16 v[74:77], v[196:199], v[172:175], v[74:77]
	v_mfma_f32_16x16x32_bf16 v[70:73], v[188:191], v[180:183], v[70:73]
	v_mfma_f32_16x16x32_bf16 v[66:69], v[196:199], v[180:183], v[66:69]
	v_mfma_f32_16x16x32_bf16 v[110:113], v[192:195], v[160:163], v[110:113]
	v_mfma_f32_16x16x32_bf16 v[106:109], v[210:213], v[160:163], v[106:109]
	v_mfma_f32_16x16x32_bf16 v[102:105], v[192:195], v[168:171], v[102:105]
	v_mfma_f32_16x16x32_bf16 v[98:101], v[210:213], v[168:171], v[98:101]
	v_mfma_f32_16x16x32_bf16 v[78:81], v[192:195], v[176:179], v[78:81]
	v_mfma_f32_16x16x32_bf16 v[74:77], v[210:213], v[176:179], v[74:77]
	v_mfma_f32_16x16x32_bf16 v[70:73], v[192:195], v[184:187], v[70:73]
	v_mfma_f32_16x16x32_bf16 v[66:69], v[210:213], v[184:187], v[66:69]
	s_setprio 0
	s_mov_b32 m0, s51
	v_lshl_add_u64 v[218:219], s[46:47], 0, v[0:1]
	s_barrier
	ds_read_b128 v[156:159], v147 offset:16384
	ds_read_b128 v[160:163], v147 offset:17408
	ds_read_b128 v[164:167], v147 offset:18432
	ds_read_b128 v[168:171], v147 offset:19456
	ds_read_b128 v[172:175], v147 offset:20480
	ds_read_b128 v[176:179], v147 offset:21504
	ds_read_b128 v[180:183], v147 offset:22528
	ds_read_b128 v[184:187], v147 offset:23552
	global_load_lds_dwordx4 v[218:219], off
	v_lshl_add_u64 v[220:221], s[46:47], 0, v[130:131]
	s_mov_b32 m0, s52
	s_nop 0
	global_load_lds_dwordx4 v[220:221], off
	s_waitcnt vmcnt(10)
	s_barrier
	s_waitcnt lgkmcnt(0)
	s_setprio 1
	s_waitcnt lgkmcnt(0)
	v_mfma_f32_16x16x32_bf16 v[62:65], v[136:139], v[156:159], v[62:65]
	v_mfma_f32_16x16x32_bf16 v[58:61], v[148:151], v[156:159], v[58:61]
	v_mfma_f32_16x16x32_bf16 v[54:57], v[136:139], v[164:167], v[54:57]
	v_mfma_f32_16x16x32_bf16 v[50:53], v[148:151], v[164:167], v[50:53]
	v_mfma_f32_16x16x32_bf16 v[30:33], v[136:139], v[172:175], v[30:33]
	v_mfma_f32_16x16x32_bf16 v[26:29], v[148:151], v[172:175], v[26:29]
	v_mfma_f32_16x16x32_bf16 v[22:25], v[136:139], v[180:183], v[22:25]
	v_mfma_f32_16x16x32_bf16 v[18:21], v[148:151], v[180:183], v[18:21]
	v_mfma_f32_16x16x32_bf16 v[62:65], v[140:143], v[160:163], v[62:65]
	v_mfma_f32_16x16x32_bf16 v[58:61], v[152:155], v[160:163], v[58:61]
	v_mfma_f32_16x16x32_bf16 v[54:57], v[140:143], v[168:171], v[54:57]
	v_mfma_f32_16x16x32_bf16 v[50:53], v[152:155], v[168:171], v[50:53]
	v_mfma_f32_16x16x32_bf16 v[30:33], v[140:143], v[176:179], v[30:33]
	v_mfma_f32_16x16x32_bf16 v[26:29], v[152:155], v[176:179], v[26:29]
	v_mfma_f32_16x16x32_bf16 v[22:25], v[140:143], v[184:187], v[22:25]
	v_mfma_f32_16x16x32_bf16 v[18:21], v[152:155], v[184:187], v[18:21]
	s_setprio 0
	s_barrier
	s_add_u32 s0, s44, 0x40000
	s_addc_u32 s1, s45, 0
	s_add_i32 s11, s61, s50
	v_lshl_add_u64 v[136:137], s[0:1], 0, v[0:1]
	s_mov_b32 m0, s11
	s_nop 0
	global_load_lds_dwordx4 v[136:137], off
	v_lshl_add_u64 v[136:137], s[0:1], 0, v[130:131]
	s_add_i32 m0, s11, 0x2000
	s_nop 0
	global_load_lds_dwordx4 v[136:137], off
	v_add_u32_e32 v152, 0x18000, v145
	ds_read_b128 v[136:139], v152
	ds_read_b128 v[140:143], v152 offset:1024
	ds_read_b128 v[148:151], v152 offset:2048
	ds_read_b128 v[152:155], v152 offset:3072
	s_waitcnt vmcnt(6)
	s_barrier
	s_setprio 1
	v_mfma_f32_16x16x32_bf16 v[46:49], v[188:191], v[156:159], v[46:49]
	v_mfma_f32_16x16x32_bf16 v[42:45], v[196:199], v[156:159], v[42:45]
	v_mfma_f32_16x16x32_bf16 v[38:41], v[188:191], v[164:167], v[38:41]
	v_mfma_f32_16x16x32_bf16 v[34:37], v[196:199], v[164:167], v[34:37]
	v_mfma_f32_16x16x32_bf16 v[14:17], v[188:191], v[172:175], v[14:17]
	v_mfma_f32_16x16x32_bf16 v[10:13], v[196:199], v[172:175], v[10:13]
	v_mfma_f32_16x16x32_bf16 v[6:9], v[188:191], v[180:183], v[6:9]
	v_mfma_f32_16x16x32_bf16 v[2:5], v[196:199], v[180:183], v[2:5]
	v_mfma_f32_16x16x32_bf16 v[46:49], v[192:195], v[160:163], v[46:49]
	v_mfma_f32_16x16x32_bf16 v[42:45], v[210:213], v[160:163], v[42:45]
	v_mfma_f32_16x16x32_bf16 v[38:41], v[192:195], v[168:171], v[38:41]
	v_mfma_f32_16x16x32_bf16 v[34:37], v[210:213], v[168:171], v[34:37]
	v_mfma_f32_16x16x32_bf16 v[14:17], v[192:195], v[176:179], v[14:17]
	v_mfma_f32_16x16x32_bf16 v[10:13], v[210:213], v[176:179], v[10:13]
	v_mfma_f32_16x16x32_bf16 v[6:9], v[192:195], v[184:187], v[6:9]
	v_mfma_f32_16x16x32_bf16 v[2:5], v[210:213], v[184:187], v[2:5]
	s_setprio 0
	s_add_i32 s11, 0, 0x18000
	s_barrier
	s_add_u32 s0, s46, 0x40000
	s_addc_u32 s1, s47, 0
	s_mov_b32 m0, s53
	v_lshl_add_u64 v[188:189], s[0:1], 0, v[0:1]
	ds_read_b128 v[156:159], v147 offset:32768
	ds_read_b128 v[160:163], v147 offset:33792
	ds_read_b128 v[164:167], v147 offset:34816
	ds_read_b128 v[168:171], v147 offset:35840
	ds_read_b128 v[172:175], v147 offset:36864
	ds_read_b128 v[176:179], v147 offset:37888
	ds_read_b128 v[180:183], v147 offset:38912
	ds_read_b128 v[184:187], v147 offset:39936
	global_load_lds_dwordx4 v[188:189], off
	v_lshl_add_u64 v[188:189], s[0:1], 0, v[130:131]
	s_mov_b32 m0, s54
	s_nop 0
	global_load_lds_dwordx4 v[188:189], off
	s_waitcnt lgkmcnt(8)
	s_barrier
; #define PG8_STAGE(bufoff, gbase, voff) do { _Pragma("unroll") for (int _i = 0; _i < 2; ++_i) \
;         __builtin_amdgcn_global_load_lds((const unsigned*)((const char*)(gbase) + (voff)[_i]), (LAS unsigned*)(lds + (bufoff) + ldsw + _i * 8192), 16, 0, 0); } while (0)
; #define PG8_LDA(dst, b, h) do { _Pragma("unroll") for (int m = 0; m < 4; ++m) _Pragma("unroll") for (int k = 0; k < 2; ++k) dst[m][k] = *(const LAS bf16x8*)(lds + PG8_SA(b, h) + aoff + m * 2048 + k * 1024); } while (0)
; #define PG8_LDB(dst, b, h) do { _Pragma("unroll") for (int n = 0; n < 2; ++n) _Pragma("unroll") for (int k = 0; k < 2; ++k) dst[n][k] = *(const LAS bf16x8*)(lds + PG8_SB(b, h) + boff + n * 2048 + k * 1024); } while (0)
; #define PG8_MMA(ai, bj, At, Bt) do { __builtin_amdgcn_s_setprio(1); _Pragma("unroll") for (int m = 0; m < 4; ++m) _Pragma("unroll") for (int n = 0; n < 2; ++n) _Pragma("unroll") for (int k = 0; k < 2; ++k) \
;         acc[ai][bj][m][n] = __builtin_amdgcn_mfma_f32_16x16x32_bf16(Bt[n][k], At[m][k], acc[ai][bj][m][n], 0, 0, 0); __builtin_amdgcn_s_setprio(0); } while (0)
; #define PG8_WAIT_V(n) asm volatile("s_waitcnt vmcnt(" #n ")" ::: "memory")
; #define PG8_WAIT_L(n) asm volatile("s_waitcnt lgkmcnt(" #n ")" ::: "memory")
; #define PG8_BAR __builtin_amdgcn_s_barrier()
; #define PG8_SCHED __builtin_amdgcn_sched_barrier(0)
; #define PG8_LDA(dst, b, h) do { _Pragma("unroll") for (int m = 0; m < 4; ++m) _Pragma("unroll") for (int k = 0; k < 2; ++k) dst[m][k] = *(const LAS bf16x8*)(lds + PG8_SA(b, h) + aoff + m * 2048 + k * 1024); } while (0)
; #define PG8_WAIT_V(n) asm volatile("s_waitcnt vmcnt(" #n ")" ::: "memory")
; #define PG8_WAIT_L(n) asm volatile("s_waitcnt lgkmcnt(" #n ")" ::: "memory")
; template <class Epi, class Sched>
; DI void gemm_phase(LAS unsigned char* lds, const Gemm g, const Sched& S, const Epi& E) {
;     ...
;             PG8_WAIT_L(8); PG8_BAR; PG8_WAIT_L(0); PG8_MMA(0, 0, At, B0); PG8_BAR; PG8_SCHED;
;             PG8_LDB(B1, 1, 1); PG8_STAGE(PG8_SB(1, 0), b3, voffB);
;             PG8_BAR; PG8_WAIT_L(0); PG8_MMA(0, 1, At, B1); PG8_BAR;
;             PG8_LDA(At, 1, 1); PG8_STAGE(PG8_SA(1, 0), a3, voffA);
;             PG8_BAR; PG8_WAIT_L(0); PG8_MMA(1, 0, At, B0); PG8_BAR; PG8_SCHED;
;             PG8_STAGE(PG8_SB(1, 1), b3 + hstepB, voffB);
;             PG8_WAIT_V(6); PG8_BAR; PG8_MMA(1, 1, At, B1); PG8_BAR;
;         }
	s_waitcnt lgkmcnt(0)
	s_setprio 1
	s_waitcnt lgkmcnt(0)
	v_mfma_f32_16x16x32_bf16 v[126:129], v[136:139], v[156:159], v[126:129]
	v_mfma_f32_16x16x32_bf16 v[122:125], v[148:151], v[156:159], v[122:125]
	v_mfma_f32_16x16x32_bf16 v[118:121], v[136:139], v[164:167], v[118:121]
	v_mfma_f32_16x16x32_bf16 v[114:117], v[148:151], v[164:167], v[114:117]
	v_mfma_f32_16x16x32_bf16 v[94:97], v[136:139], v[172:175], v[94:97]
	v_mfma_f32_16x16x32_bf16 v[90:93], v[148:151], v[172:175], v[90:93]
	v_mfma_f32_16x16x32_bf16 v[86:89], v[136:139], v[180:183], v[86:89]
	v_mfma_f32_16x16x32_bf16 v[82:85], v[148:151], v[180:183], v[82:85]
	v_mfma_f32_16x16x32_bf16 v[126:129], v[140:143], v[160:163], v[126:129]
	v_mfma_f32_16x16x32_bf16 v[122:125], v[152:155], v[160:163], v[122:125]
	v_mfma_f32_16x16x32_bf16 v[118:121], v[140:143], v[168:171], v[118:121]
	v_mfma_f32_16x16x32_bf16 v[114:117], v[152:155], v[168:171], v[114:117]
	v_mfma_f32_16x16x32_bf16 v[94:97], v[140:143], v[176:179], v[94:97]
	v_mfma_f32_16x16x32_bf16 v[90:93], v[152:155], v[176:179], v[90:93]
	v_mfma_f32_16x16x32_bf16 v[86:89], v[140:143], v[184:187], v[86:89]
	v_mfma_f32_16x16x32_bf16 v[82:85], v[152:155], v[184:187], v[82:85]
	s_setprio 0
	s_barrier
	s_add_i32 s46, 0, 0x1c000
	s_add_i32 s0, s11, s50
	v_add_u32_e32 v210, s46, v145
	v_lshl_add_u64 v[214:215], v[214:215], 0, s[16:17]
	s_mov_b32 m0, s0
	ds_read_b128 v[188:191], v210
	ds_read_b128 v[192:195], v210 offset:1024
	ds_read_b128 v[196:199], v210 offset:2048
	ds_read_b128 v[210:213], v210 offset:3072
	global_load_lds_dwordx4 v[214:215], off
	v_lshl_add_u64 v[214:215], v[216:217], 0, s[16:17]
	s_add_i32 m0, s0, 0x2000
	s_nop 0
	global_load_lds_dwordx4 v[214:215], off
	s_barrier
	s_waitcnt lgkmcnt(0)
	s_setprio 1
	s_waitcnt lgkmcnt(0)
	v_mfma_f32_16x16x32_bf16 v[110:113], v[188:191], v[156:159], v[110:113]
	v_mfma_f32_16x16x32_bf16 v[106:109], v[196:199], v[156:159], v[106:109]
	v_mfma_f32_16x16x32_bf16 v[102:105], v[188:191], v[164:167], v[102:105]
	v_mfma_f32_16x16x32_bf16 v[98:101], v[196:199], v[164:167], v[98:101]
	v_mfma_f32_16x16x32_bf16 v[78:81], v[188:191], v[172:175], v[78:81]
	v_mfma_f32_16x16x32_bf16 v[74:77], v[196:199], v[172:175], v[74:77]
	v_mfma_f32_16x16x32_bf16 v[70:73], v[188:191], v[180:183], v[70:73]
	v_mfma_f32_16x16x32_bf16 v[66:69], v[196:199], v[180:183], v[66:69]
	v_mfma_f32_16x16x32_bf16 v[110:113], v[192:195], v[160:163], v[110:113]
	v_mfma_f32_16x16x32_bf16 v[106:109], v[210:213], v[160:163], v[106:109]
	v_mfma_f32_16x16x32_bf16 v[102:105], v[192:195], v[168:171], v[102:105]
	v_mfma_f32_16x16x32_bf16 v[98:101], v[210:213], v[168:171], v[98:101]
	v_mfma_f32_16x16x32_bf16 v[78:81], v[192:195], v[176:179], v[78:81]
	v_mfma_f32_16x16x32_bf16 v[74:77], v[210:213], v[176:179], v[74:77]
	v_mfma_f32_16x16x32_bf16 v[70:73], v[192:195], v[184:187], v[70:73]
	v_mfma_f32_16x16x32_bf16 v[66:69], v[210:213], v[184:187], v[66:69]
	s_setprio 0
	s_mov_b32 m0, s55
	v_lshl_add_u64 v[214:215], v[218:219], 0, s[16:17]
	s_barrier
	ds_read_b128 v[156:159], v147 offset:49152
	ds_read_b128 v[160:163], v147 offset:50176
	ds_read_b128 v[164:167], v147 offset:51200
	ds_read_b128 v[168:171], v147 offset:52224
	ds_read_b128 v[172:175], v147 offset:53248
	ds_read_b128 v[176:179], v147 offset:54272
	ds_read_b128 v[180:183], v147 offset:55296
	ds_read_b128 v[184:187], v147 offset:56320
	global_load_lds_dwordx4 v[214:215], off
	v_lshl_add_u64 v[214:215], v[220:221], 0, s[16:17]
	s_mov_b32 m0, s56
	s_nop 0
	global_load_lds_dwordx4 v[214:215], off
	s_waitcnt vmcnt(10)
	s_barrier
	s_waitcnt lgkmcnt(0)
	s_setprio 1
	s_waitcnt lgkmcnt(0)
	v_mfma_f32_16x16x32_bf16 v[62:65], v[136:139], v[156:159], v[62:65]
	v_mfma_f32_16x16x32_bf16 v[58:61], v[148:151], v[156:159], v[58:61]
	v_mfma_f32_16x16x32_bf16 v[54:57], v[136:139], v[164:167], v[54:57]
	v_mfma_f32_16x16x32_bf16 v[50:53], v[148:151], v[164:167], v[50:53]
	v_mfma_f32_16x16x32_bf16 v[30:33], v[136:139], v[172:175], v[30:33]
	v_mfma_f32_16x16x32_bf16 v[26:29], v[148:151], v[172:175], v[26:29]
	v_mfma_f32_16x16x32_bf16 v[22:25], v[136:139], v[180:183], v[22:25]
	v_mfma_f32_16x16x32_bf16 v[18:21], v[148:151], v[180:183], v[18:21]
	v_mfma_f32_16x16x32_bf16 v[62:65], v[140:143], v[160:163], v[62:65]
	v_mfma_f32_16x16x32_bf16 v[58:61], v[152:155], v[160:163], v[58:61]
	v_mfma_f32_16x16x32_bf16 v[54:57], v[140:143], v[168:171], v[54:57]
	v_mfma_f32_16x16x32_bf16 v[50:53], v[152:155], v[168:171], v[50:53]
	v_mfma_f32_16x16x32_bf16 v[30:33], v[140:143], v[176:179], v[30:33]
	v_mfma_f32_16x16x32_bf16 v[26:29], v[152:155], v[176:179], v[26:29]
	v_mfma_f32_16x16x32_bf16 v[22:25], v[140:143], v[184:187], v[22:25]
	v_mfma_f32_16x16x32_bf16 v[18:21], v[152:155], v[184:187], v[18:21]
	s_setprio 0
	s_barrier
	s_add_u32 s0, s44, 0x40080
	s_addc_u32 s1, s45, 0
	s_add_i32 s11, s46, s50
	v_lshl_add_u64 v[136:137], s[0:1], 0, v[0:1]
	s_mov_b32 m0, s11
	s_nop 0
	global_load_lds_dwordx4 v[136:137], off
	v_lshl_add_u64 v[136:137], s[0:1], 0, v[130:131]
	s_add_i32 m0, s11, 0x2000
	s_nop 0
	global_load_lds_dwordx4 v[136:137], off
	v_add_u32_e32 v152, 0x10000, v145
	ds_read_b128 v[136:139], v152
	ds_read_b128 v[140:143], v152 offset:1024
	ds_read_b128 v[148:151], v152 offset:2048
	ds_read_b128 v[152:155], v152 offset:3072
	s_waitcnt vmcnt(6)
	s_barrier
; #define PG8_STAGE(bufoff, gbase, voff) do { _Pragma("unroll") for (int _i = 0; _i < 2; ++_i) \
;         __builtin_amdgcn_global_load_lds((const unsigned*)((const char*)(gbase) + (voff)[_i]), (LAS unsigned*)(lds + (bufoff) + ldsw + _i * 8192), 16, 0, 0); } while (0)
; #define PG8_MMA(ai, bj, At, Bt) do { __builtin_amdgcn_s_setprio(1); _Pragma("unroll") for (int m = 0; m < 4; ++m) _Pragma("unroll") for (int n = 0; n < 2; ++n) _Pragma("unroll") for (int k = 0; k < 2; ++k) \
;         acc[ai][bj][m][n] = __builtin_amdgcn_mfma_f32_16x16x32_bf16(Bt[n][k], At[m][k], acc[ai][bj][m][n], 0, 0, 0); __builtin_amdgcn_s_setprio(0); } while (0)
; #define PG8_WAIT_V(n) asm volatile("s_waitcnt vmcnt(" #n ")" ::: "memory")
; #define PG8_BAR __builtin_amdgcn_s_barrier()
; #define PG8_MMA(ai, bj, At, Bt) do { __builtin_amdgcn_s_setprio(1); _Pragma("unroll") for (int m = 0; m < 4; ++m) _Pragma("unroll") for (int n = 0; n < 2; ++n) _Pragma("unroll") for (int k = 0; k < 2; ++k)         acc[ai][bj][m][n] = __builtin_amdgcn_mfma_f32_16x16x32_bf16(Bt[n][k], At[m][k], acc[ai][bj][m][n], 0, 0, 0); __builtin_amdgcn_s_setprio(0); } while (0)
; template <class Epi, class Sched>
; DI void gemm_phase(LAS unsigned char* lds, const Gemm g, const Sched& S, const Epi& E) {
;     ...
;             PG8_STAGE(PG8_SB(1, 1), b3 + hstepB, voffB);
;             PG8_WAIT_V(6); PG8_BAR; PG8_MMA(1, 1, At, B1); PG8_BAR;
;         }
;   DI void operator()(const f32x4 (&acc)[2][2][4][2], const Unit& u, int wr, int wc, int fr, int fq) const {
;     const int row0 = u.pm * BM + wr * 64 + fr, col0 = u.pn * BM + wc * 32 + 4 * fq;
; #pragma unroll
;     for (int ai = 0; ai < 2; ++ai)
; #pragma unroll
;       for (int mp = 0; mp < 2; ++mp) {
;         f32x4 xv[2][2][2];
; #pragma unroll
;         for (int mm = 0; mm < 2; ++mm)
; #pragma unroll
;           for (int bj = 0; bj < 2; ++bj)
; #pragma unroll
;             for (int n = 0; n < 2; ++n)
;               xv[mm][bj][n] = *(const f32x4*)(X + (size_t)(row0 + ai * HALF + (mp * 2 + mm) * 16) * 1024 + col0 + bj * HALF + n * 16);
; #pragma unroll
;         for (int mm = 0; mm < 2; ++mm)
; #pragma unroll
;           for (int bj = 0; bj < 2; ++bj)
; #pragma unroll
;             for (int n = 0; n < 2; ++n)
;               *(f32x4*)(O + (size_t)(row0 + ai * HALF + (mp * 2 + mm) * 16) * 1024 + col0 + bj * HALF + n * 16) = xv[mm][bj][n] + acc[ai][bj][mp * 2 + mm][n];
;       }
	s_setprio 1
	v_mfma_f32_16x16x32_bf16 v[46:49], v[188:191], v[156:159], v[46:49]
	v_mfma_f32_16x16x32_bf16 v[42:45], v[196:199], v[156:159], v[42:45]
	v_mfma_f32_16x16x32_bf16 v[38:41], v[188:191], v[164:167], v[38:41]
	v_mfma_f32_16x16x32_bf16 v[34:37], v[196:199], v[164:167], v[34:37]
	v_mfma_f32_16x16x32_bf16 v[14:17], v[188:191], v[172:175], v[14:17]
	v_mfma_f32_16x16x32_bf16 v[10:13], v[196:199], v[172:175], v[10:13]
	v_mfma_f32_16x16x32_bf16 v[6:9], v[188:191], v[180:183], v[6:9]
	v_mfma_f32_16x16x32_bf16 v[2:5], v[196:199], v[180:183], v[2:5]
	v_mfma_f32_16x16x32_bf16 v[46:49], v[192:195], v[160:163], v[46:49]
	v_mfma_f32_16x16x32_bf16 v[42:45], v[210:213], v[160:163], v[42:45]
	v_mfma_f32_16x16x32_bf16 v[38:41], v[192:195], v[168:171], v[38:41]
	v_mfma_f32_16x16x32_bf16 v[34:37], v[210:213], v[168:171], v[34:37]
	v_mfma_f32_16x16x32_bf16 v[14:17], v[192:195], v[176:179], v[14:17]
	v_mfma_f32_16x16x32_bf16 v[10:13], v[210:213], v[176:179], v[10:13]
	v_mfma_f32_16x16x32_bf16 v[6:9], v[192:195], v[184:187], v[6:9]
	v_mfma_f32_16x16x32_bf16 v[2:5], v[210:213], v[184:187], v[2:5]
	s_setprio 0
	s_add_i32 s60, s60, 2
	s_add_u32 s58, s58, 0x100
	s_addc_u32 s59, s59, 0
	s_add_u32 s42, s42, 0x100
	s_addc_u32 s43, s43, 0
	s_cmp_gt_u32 s60, 13
	s_barrier
	s_cbranch_scc0 .LBB0_1039
	s_waitcnt lgkmcnt(0)
	v_lshl_or_b32 v136, s41, 8, v146
	v_lshl_add_u32 v142, s40, 8, v144
	v_ashrrev_i32_e32 v137, 31, v136
	v_lshlrev_b64 v[136:137], 2, v[136:137]
	v_ashrrev_i32_e32 v143, 31, v142
	v_or_b32_e32 v164, 16, v142
	v_lshl_add_u64 v[138:139], s[2:3], 0, v[136:137]
	v_lshlrev_b64 v[140:141], 12, v[142:143]
	v_ashrrev_i32_e32 v165, 31, v164
	v_lshl_add_u64 v[160:161], v[138:139], 0, v[140:141]
	v_lshlrev_b64 v[180:181], 12, v[164:165]
	global_load_dwordx4 v[148:151], v[160:161], off
	global_load_dwordx4 v[152:155], v[160:161], off offset:64
	global_load_dwordx4 v[156:159], v[160:161], off offset:512
	s_nop 0
	global_load_dwordx4 v[160:163], v[160:161], off offset:576
	v_lshl_add_u64 v[176:177], v[138:139], 0, v[180:181]
	global_load_dwordx4 v[164:167], v[176:177], off
	global_load_dwordx4 v[168:171], v[176:177], off offset:64
	global_load_dwordx4 v[172:175], v[176:177], off offset:512
	s_nop 0
	global_load_dwordx4 v[176:179], v[176:177], off offset:576
	s_mov_b64 s[40:41], 0x80000
	s_mov_b64 s[0:1], 0x90000
	s_and_b64 vcc, exec, s[36:37]
	s_mov_b64 s[42:43], s[38:39]
	s_mov_b64 s[44:45], s[34:35]
	s_waitcnt vmcnt(0)
	v_pk_add_f32 v[126:127], v[126:127], v[148:149]
	v_lshl_add_u64 v[148:149], s[4:5], 0, v[140:141]
	v_lshl_add_u64 v[148:149], v[148:149], 0, v[136:137]
	v_pk_add_f32 v[112:113], v[112:113], v[158:159]
	v_pk_add_f32 v[110:111], v[110:111], v[156:157]
	global_store_dwordx4 v[148:149], v[110:113], off offset:512
	v_pk_add_f32 v[100:101], v[100:101], v[178:179]
	v_pk_add_f32 v[98:99], v[98:99], v[176:177]
	v_lshl_add_u64 v[110:111], s[4:5], 0, v[180:181]
	v_lshl_add_u64 v[110:111], v[110:111], 0, v[136:137]
	v_pk_add_f32 v[108:109], v[108:109], v[162:163]
	v_pk_add_f32 v[106:107], v[106:107], v[160:161]
	global_store_dwordx4 v[110:111], v[98:101], off offset:576
	v_pk_add_f32 v[128:129], v[128:129], v[150:151]
	v_pk_add_f32 v[124:125], v[124:125], v[154:155]
	v_or_b32_e32 v98, 32, v142
	v_pk_add_f32 v[122:123], v[122:123], v[152:153]
	global_store_dwordx4 v[148:149], v[106:109], off offset:576
	v_ashrrev_i32_e32 v99, 31, v98
	global_store_dwordx4 v[148:149], v[126:129], off
	v_pk_add_f32 v[108:109], v[120:121], v[166:167]
	v_pk_add_f32 v[106:107], v[118:119], v[164:165]
	global_store_dwordx4 v[148:149], v[122:125], off offset:64
	global_store_dwordx4 v[110:111], v[106:109], off
	v_pk_add_f32 v[104:105], v[104:105], v[174:175]
	v_pk_add_f32 v[102:103], v[102:103], v[172:173]
	v_pk_add_f32 v[108:109], v[116:117], v[170:171]
	v_pk_add_f32 v[106:107], v[114:115], v[168:169]
	v_lshlrev_b64 v[148:149], 12, v[98:99]
	v_or_b32_e32 v114, 48, v142
	global_store_dwordx4 v[110:111], v[106:109], off offset:64
	global_store_dwordx4 v[110:111], v[102:105], off offset:512
	v_lshl_add_u64 v[110:111], v[138:139], 0, v[148:149]
	v_ashrrev_i32_e32 v115, 31, v114
	global_load_dwordx4 v[98:101], v[110:111], off
	global_load_dwordx4 v[102:105], v[110:111], off offset:64
	global_load_dwordx4 v[106:109], v[110:111], off offset:512
	s_nop 0
	global_load_dwordx4 v[110:113], v[110:111], off offset:576
	v_lshlrev_b64 v[142:143], 12, v[114:115]
	v_lshl_add_u64 v[126:127], v[138:139], 0, v[142:143]
	global_load_dwordx4 v[114:117], v[126:127], off
	global_load_dwordx4 v[118:121], v[126:127], off offset:64
	global_load_dwordx4 v[122:125], v[126:127], off offset:512
	s_nop 0
	global_load_dwordx4 v[126:129], v[126:127], off offset:576
	s_waitcnt vmcnt(0)
;   DI void operator()(const f32x4 (&acc)[2][2][4][2], const Unit& u, int wr, int wc, int fr, int fq) const {
;     ...
;     for (int ai = 0; ai < 2; ++ai)
; #pragma unroll
;       for (int mp = 0; mp < 2; ++mp) {
;         f32x4 xv[2][2][2];
; #pragma unroll
;         for (int mm = 0; mm < 2; ++mm)
; #pragma unroll
;           for (int bj = 0; bj < 2; ++bj)
; #pragma unroll
;             for (int n = 0; n < 2; ++n)
;               xv[mm][bj][n] = *(const f32x4*)(X + (size_t)(row0 + ai * HALF + (mp * 2 + mm) * 16) * 1024 + col0 + bj * HALF + n * 16);
; #pragma unroll
;         for (int mm = 0; mm < 2; ++mm)
; #pragma unroll
;           for (int bj = 0; bj < 2; ++bj)
; #pragma unroll
;             for (int n = 0; n < 2; ++n)
;               *(f32x4*)(O + (size_t)(row0 + ai * HALF + (mp * 2 + mm) * 16) * 1024 + col0 + bj * HALF + n * 16) = xv[mm][bj][n] + acc[ai][bj][mp * 2 + mm][n];
;       }
	v_pk_add_f32 v[94:95], v[94:95], v[98:99]
	v_lshl_add_u64 v[98:99], s[4:5], 0, v[148:149]
	v_lshl_add_u64 v[98:99], v[98:99], 0, v[136:137]
	v_pk_add_f32 v[80:81], v[80:81], v[108:109]
	v_pk_add_f32 v[78:79], v[78:79], v[106:107]
	global_store_dwordx4 v[98:99], v[78:81], off offset:512
	v_pk_add_f32 v[76:77], v[76:77], v[112:113]
	v_pk_add_f32 v[74:75], v[74:75], v[110:111]
	v_lshl_add_u64 v[78:79], s[4:5], 0, v[142:143]
	v_pk_add_f32 v[96:97], v[96:97], v[100:101]
	v_pk_add_f32 v[92:93], v[92:93], v[104:105]
	v_pk_add_f32 v[90:91], v[90:91], v[102:103]
	global_store_dwordx4 v[98:99], v[74:77], off offset:576
	v_lshl_add_u64 v[78:79], v[78:79], 0, v[136:137]
	global_store_dwordx4 v[98:99], v[94:97], off
	v_pk_add_f32 v[76:77], v[88:89], v[116:117]
	v_pk_add_f32 v[74:75], v[86:87], v[114:115]
	global_store_dwordx4 v[98:99], v[90:93], off offset:64
	global_store_dwordx4 v[78:79], v[74:77], off
	v_pk_add_f32 v[72:73], v[72:73], v[124:125]
	v_pk_add_f32 v[70:71], v[70:71], v[122:123]
	v_pk_add_f32 v[76:77], v[84:85], v[120:121]
	v_pk_add_f32 v[74:75], v[82:83], v[118:119]
	v_pk_add_f32 v[68:69], v[68:69], v[128:129]
	v_pk_add_f32 v[66:67], v[66:67], v[126:127]
	v_lshl_add_u64 v[98:99], v[140:141], 0, s[40:41]
	global_store_dwordx4 v[78:79], v[74:77], off offset:64
	global_store_dwordx4 v[78:79], v[70:73], off offset:512
	global_store_dwordx4 v[78:79], v[66:69], off offset:576
	v_lshl_add_u64 v[78:79], v[138:139], 0, v[98:99]
	global_load_dwordx4 v[66:69], v[78:79], off
	global_load_dwordx4 v[70:73], v[78:79], off offset:64
	global_load_dwordx4 v[74:77], v[78:79], off offset:512
	s_nop 0
	global_load_dwordx4 v[78:81], v[78:79], off offset:576
	v_lshl_add_u64 v[100:101], v[140:141], 0, s[0:1]
	v_lshl_add_u64 v[94:95], v[138:139], 0, v[100:101]
	global_load_dwordx4 v[82:85], v[94:95], off
	global_load_dwordx4 v[86:89], v[94:95], off offset:64
	global_load_dwordx4 v[90:93], v[94:95], off offset:512
	s_nop 0
	global_load_dwordx4 v[94:97], v[94:95], off offset:576
	s_mov_b64 s[40:41], 0xa0000
	s_mov_b64 s[0:1], 0xb0000
	s_waitcnt vmcnt(0)
	v_pk_add_f32 v[62:63], v[62:63], v[66:67]
	v_lshl_add_u64 v[66:67], s[4:5], 0, v[98:99]
	v_lshl_add_u64 v[66:67], v[66:67], 0, v[136:137]
	v_pk_add_f32 v[48:49], v[48:49], v[76:77]
	v_pk_add_f32 v[46:47], v[46:47], v[74:75]
	global_store_dwordx4 v[66:67], v[46:49], off offset:512
	v_pk_add_f32 v[44:45], v[44:45], v[80:81]
	v_pk_add_f32 v[42:43], v[42:43], v[78:79]
	v_lshl_add_u64 v[46:47], s[4:5], 0, v[100:101]
	v_pk_add_f32 v[64:65], v[64:65], v[68:69]
	v_pk_add_f32 v[60:61], v[60:61], v[72:73]
	v_pk_add_f32 v[58:59], v[58:59], v[70:71]
	global_store_dwordx4 v[66:67], v[42:45], off offset:576
	v_lshl_add_u64 v[46:47], v[46:47], 0, v[136:137]
	global_store_dwordx4 v[66:67], v[62:65], off
	v_pk_add_f32 v[44:45], v[56:57], v[84:85]
	v_pk_add_f32 v[42:43], v[54:55], v[82:83]
	global_store_dwordx4 v[66:67], v[58:61], off offset:64
	global_store_dwordx4 v[46:47], v[42:45], off
	v_pk_add_f32 v[40:41], v[40:41], v[92:93]
	v_pk_add_f32 v[38:39], v[38:39], v[90:91]
	v_pk_add_f32 v[44:45], v[52:53], v[88:89]
	v_pk_add_f32 v[42:43], v[50:51], v[86:87]
	v_pk_add_f32 v[36:37], v[36:37], v[96:97]
	v_pk_add_f32 v[34:35], v[34:35], v[94:95]
	v_lshl_add_u64 v[66:67], v[140:141], 0, s[40:41]
	global_store_dwordx4 v[46:47], v[42:45], off offset:64
	global_store_dwordx4 v[46:47], v[38:41], off offset:512
	global_store_dwordx4 v[46:47], v[34:37], off offset:576
	v_lshl_add_u64 v[46:47], v[138:139], 0, v[66:67]
	global_load_dwordx4 v[34:37], v[46:47], off
	global_load_dwordx4 v[38:41], v[46:47], off offset:64
	global_load_dwordx4 v[42:45], v[46:47], off offset:512
	s_nop 0
	global_load_dwordx4 v[46:49], v[46:47], off offset:576
	v_lshl_add_u64 v[68:69], v[140:141], 0, s[0:1]
	v_lshl_add_u64 v[62:63], v[138:139], 0, v[68:69]
	global_load_dwordx4 v[50:53], v[62:63], off
	global_load_dwordx4 v[54:57], v[62:63], off offset:64
	global_load_dwordx4 v[58:61], v[62:63], off offset:512
	s_nop 0
	global_load_dwordx4 v[62:65], v[62:63], off offset:576
	s_mov_b32 s41, s8
	s_mov_b32 s40, s12
	s_waitcnt vmcnt(0)
	v_pk_add_f32 v[30:31], v[30:31], v[34:35]
	v_lshl_add_u64 v[34:35], s[4:5], 0, v[66:67]
	v_lshl_add_u64 v[34:35], v[34:35], 0, v[136:137]
	v_pk_add_f32 v[16:17], v[16:17], v[44:45]
	v_pk_add_f32 v[14:15], v[14:15], v[42:43]
	global_store_dwordx4 v[34:35], v[14:17], off offset:512
	v_pk_add_f32 v[12:13], v[12:13], v[48:49]
	v_pk_add_f32 v[10:11], v[10:11], v[46:47]
	v_lshl_add_u64 v[14:15], s[4:5], 0, v[68:69]
	global_store_dwordx4 v[34:35], v[10:13], off offset:576
	v_lshl_add_u64 v[14:15], v[14:15], 0, v[136:137]
	v_pk_add_f32 v[32:33], v[32:33], v[36:37]
	v_pk_add_f32 v[12:13], v[24:25], v[52:53]
	v_pk_add_f32 v[10:11], v[22:23], v[50:51]
	v_pk_add_f32 v[28:29], v[28:29], v[40:41]
	v_pk_add_f32 v[26:27], v[26:27], v[38:39]
	global_store_dwordx4 v[14:15], v[10:13], off
	v_pk_add_f32 v[8:9], v[8:9], v[60:61]
	v_pk_add_f32 v[6:7], v[6:7], v[58:59]
	v_pk_add_f32 v[12:13], v[20:21], v[56:57]
	v_pk_add_f32 v[10:11], v[18:19], v[54:55]
	v_pk_add_f32 v[4:5], v[4:5], v[64:65]
	v_pk_add_f32 v[2:3], v[2:3], v[62:63]
	global_store_dwordx4 v[34:35], v[30:33], off
	global_store_dwordx4 v[34:35], v[26:29], off offset:64
	global_store_dwordx4 v[14:15], v[10:13], off offset:64
	global_store_dwordx4 v[14:15], v[6:9], off offset:512
	global_store_dwordx4 v[14:15], v[2:5], off offset:576
	s_cbranch_vccz .LBB0_1032
	s_waitcnt vmcnt(0)
	s_cmpk_gt_u32 s20, 0xff
	s_cbranch_scc1 .LBB0_1043
	s_barrier
